# GEMM1: first two K tiles of the next output tile are loaded before the current tile's epilogue (registers the epilogue does not touch); epilogue store staging uses two LDS read-back tuples
# baseline (speedup 1.0000x reference)
.LBB0_202:
	s_cmp_lt_i32 s64, 3
	s_cselect_b64 s[16:17], -1, 0
	s_and_b64 s[0:1], s[16:17], s[0:1]
	s_xor_b64 s[0:1], s[0:1], -1
	s_cmpk_gt_i32 s2, 0x6ff
	s_cselect_b64 s[4:5], -1, 0
	s_or_b64 s[0:1], s[0:1], s[4:5]
	s_and_b64 vcc, exec, s[0:1]
	v_mbcnt_lo_u32_b32 v213, -1, 0
	s_cbranch_vccnz .LBB0_386
	v_and_b32_e32 v176, 63, v212
	v_and_b32_e32 v177, 31, v212
	v_bfe_u32 v178, v212, 5, 1
	v_lshrrev_b32_e32 v179, 6, v212
	v_mul_u32_u24_e32 v179, 0x1200, v179
	v_add_u32_e32 v179, 0x12000, v179
	v_mul_u32_u24_e32 v180, 0x90, v177
	v_add_u32_e32 v180, v180, v179
	v_lshl_add_u32 v202, v178, 6, v180
	v_lshl_add_u32 v203, v178, 5, v180
	v_lshrrev_b32_e32 v181, 3, v176
	v_and_b32_e32 v182, 7, v176
	v_mul_u32_u24_e32 v183, 0x240, v181
	v_add_u32_e32 v183, v183, v179
	v_lshl_add_u32 v204, v182, 4, v183
	v_lshrrev_b32_e32 v184, 2, v176
	v_and_b32_e32 v185, 3, v176
	v_mul_u32_u24_e32 v186, 0x120, v184
	v_add_u32_e32 v186, v186, v179
	v_lshl_add_u32 v205, v185, 4, v186
	v_lshlrev_b32_e32 v187, 2, v181
	v_sub_u32_e32 v187, v187, v177
	v_lshlrev_b32_e32 v188, 4, v182
	v_lshlrev_b32_e32 v189, 6, v178
	v_sub_u32_e32 v188, v188, v189
	v_lshl_add_u32 v206, v187, 10, v188
	v_ashrrev_i32_e32 v207, 31, v206
	v_lshl_add_u32 v208, v187, 7, v188
	v_ashrrev_i32_e32 v209, 31, v208
	v_lshlrev_b32_e32 v190, 1, v184
	v_sub_u32_e32 v190, v190, v177
	v_lshlrev_b32_e32 v191, 4, v185
	v_lshlrev_b32_e32 v189, 5, v178
	v_sub_u32_e32 v191, v191, v189
	v_lshl_add_u32 v210, v190, 10, v191
	v_ashrrev_i32_e32 v211, 31, v210
	s_and_b32 s0, s62, 7
	s_cmp_lg_u32 s0, 0
	s_cselect_b64 s[0:1], -1, 0
	s_ashr_i32 s44, s62, 3
	s_add_u32 s45, s96, 0x20000
	s_addc_u32 s46, s97, 0
	s_add_u32 s47, s96, 0x13a0000
	s_addc_u32 s48, s97, 0
	s_add_u32 s18, s96, 0xd3a4000
	s_addc_u32 s19, s97, 0
	s_add_u32 s20, s96, 0x73a0000
	s_addc_u32 s21, s97, 0
	s_add_u32 s22, s96, 0x8ba0000
	s_addc_u32 s23, s97, 0
	s_add_u32 s24, s96, 0xa3a0000
	s_addc_u32 s25, s97, 0
	s_add_u32 s26, s74, 0x7000000
	s_addc_u32 s27, s75, 0
	s_add_u32 s28, s74, 0x6000000
	s_addc_u32 s29, s75, 0
	s_abs_i32 s49, s62
	v_cvt_f32_u32_e32 v2, s49
	s_sub_i32 s3, 0, s49
	v_cndmask_b32_e64 v3, 0, 1, s[0:1]
	s_mov_b64 s[72:73], s[60:61]
	v_rcp_iflag_f32_e32 v2, v2
	v_mov_b32_e32 v99, 0
	s_movk_i32 s50, 0x90
	v_cmp_ne_u32_e64 s[0:1], 1, v3
	v_mul_f32_e32 v2, 0x4f7ffffe, v2
	v_cvt_u32_f32_e32 v2, v2
	s_ashr_i32 s51, s62, 31
	s_sub_i32 s52, 0, s62
	s_mov_b32 s54, 0x20000
	v_readfirstlane_b32 s4, v2
	s_mul_i32 s3, s3, s4
	s_mul_hi_u32 s3, s4, s3
	s_add_i32 s53, s4, s3
	s_mov_b32 s55, 0x40000
	s_movk_i32 s56, 0x110
	s_movk_i32 s57, 0x2000
	v_mov_b32_e32 v124, 0x358637bd
	s_mov_b32 s58, 0x800000
	s_movk_i32 s59, 0x1fe0
	s_movk_i32 s60, 0x1fc0
	v_mov_b32_e32 v125, 0x60
	v_mov_b32_e32 v126, 0x440
	v_mov_b32_e32 v127, 0x880
	v_mov_b32_e32 v128, 0xfffffa00
	v_mov_b32_e32 v129, 0xfffff800
	v_mov_b32_e32 v130, 0x3e38aa3b
	v_mbcnt_hi_u32_b32 v132, -1, v213
	v_mov_b32_e32 v133, 0xbb9e800
	v_mov_b32_e32 v134, 0x5b9f800
	s_mov_b32 s101, 0
	s_mov_b32 s61, s2
	s_branch .LBB0_205

.LBB0_208:
	s_lshl_b32 s4, s8, 8
	s_ashr_i32 s5, s4, 31
	v_mov_b32_e32 v58, v212
	s_lshl_b64 s[10:11], s[4:5], 11
	s_add_u32 s10, s45, s10
	v_ashrrev_i32_e32 v30, 3, v58
	v_ashrrev_i32_e32 v31, 31, v30
	s_addc_u32 s11, s46, s11
	v_lshlrev_b64 v[2:3], 11, v[30:31]
	v_lshlrev_b32_e32 v6, 4, v58
	v_lshl_add_u64 v[4:5], s[10:11], 0, v[2:3]
	v_and_b32_e32 v98, 0x70, v6
	v_lshl_add_u64 v[102:103], v[4:5], 0, v[98:99]
	s_mul_i32 s6, s9, 0xc0
	v_add_co_u32_e32 v106, vcc, s54, v102
	s_ashr_i32 s7, s6, 31
	s_nop 0
	v_addc_co_u32_e32 v107, vcc, 0, v103, vcc
	s_lshl_b64 s[12:13], s[6:7], 11
	v_add_co_u32_e32 v108, vcc, s55, v102
	s_add_u32 s12, s47, s12
	s_nop 0
	v_addc_co_u32_e32 v109, vcc, 0, v103, vcc
	s_mov_b32 s3, 0x60000
	s_addc_u32 s13, s48, s13
	v_add_co_u32_e32 v110, vcc, s3, v102
	v_lshl_add_u64 v[2:3], s[12:13], 0, v[2:3]
	s_nop 0
	v_addc_co_u32_e32 v111, vcc, 0, v103, vcc
	v_lshl_add_u64 v[104:105], v[2:3], 0, v[98:99]
	v_add_co_u32_e32 v112, vcc, s54, v104
	v_mad_u64_u32 v[114:115], s[10:11], v30, s50, v[98:99]
	s_nop 0
	v_addc_co_u32_e32 v113, vcc, 0, v105, vcc
	v_add_co_u32_e32 v116, vcc, s55, v104
	s_nop 0
	v_addc_co_u32_e32 v117, vcc, 0, v105, vcc
	s_cmp_eq_u32 s101, 1
	s_cbranch_scc1 .Lg1x_use
	global_load_dwordx4 v[2:5], v[102:103], off
	global_load_dwordx4 v[6:9], v[106:107], off
	global_load_dwordx4 v[10:13], v[108:109], off
	global_load_dwordx4 v[14:17], v[110:111], off
	global_load_dwordx4 v[18:21], v[104:105], off
	global_load_dwordx4 v[22:25], v[112:113], off
	global_load_dwordx4 v[26:29], v[116:117], off
	global_load_dwordx4 v[30:33], v[102:103], off offset:128
	global_load_dwordx4 v[34:37], v[106:107], off offset:128
	global_load_dwordx4 v[38:41], v[108:109], off offset:128
	global_load_dwordx4 v[42:45], v[110:111], off offset:128
	global_load_dwordx4 v[46:49], v[104:105], off offset:128
	global_load_dwordx4 v[50:53], v[112:113], off offset:128
	global_load_dwordx4 v[54:57], v[116:117], off offset:128
	s_mov_b32 s3, 0xfffffc0
	v_add_u32_e32 v119, 0x12000, v114
	s_waitcnt vmcnt(13)
	ds_write_b128 v114, v[2:5]
	s_waitcnt vmcnt(12)
	ds_write_b128 v114, v[6:9] offset:9216
	s_waitcnt vmcnt(11)
	ds_write_b128 v114, v[10:13] offset:18432
	s_waitcnt vmcnt(10)
	ds_write_b128 v114, v[14:17] offset:27648
	s_waitcnt vmcnt(9)
	ds_write_b128 v114, v[18:21] offset:36864
	s_waitcnt vmcnt(8)
	ds_write_b128 v114, v[22:25] offset:46080
	s_waitcnt vmcnt(7)
	ds_write_b128 v114, v[26:29] offset:55296
	s_branch .Lg1x_join
.Lg1x_use:
	s_mov_b32 s3, 0xfffffc0
	v_add_u32_e32 v119, 0x12000, v114
	s_waitcnt vmcnt(4)
	ds_write_b128 v114, v[214:217]
	ds_write_b128 v114, v[218:221] offset:9216
	ds_write_b128 v114, v[222:225] offset:18432
	ds_write_b128 v114, v[226:229] offset:27648
	ds_write_b128 v114, v[230:233] offset:36864
	ds_write_b128 v114, v[234:237] offset:46080
	ds_write_b128 v114, v[238:241] offset:55296
	v_mov_b32_e32 v30, v194
	v_mov_b32_e32 v31, v195
	v_mov_b32_e32 v32, v196
	v_mov_b32_e32 v33, v197
	v_mov_b32_e32 v34, v198
	v_mov_b32_e32 v35, v199
	v_mov_b32_e32 v36, v200
	v_mov_b32_e32 v37, v201
	v_mov_b32_e32 v38, v246
	v_mov_b32_e32 v39, v247
	v_mov_b32_e32 v40, v248
	v_mov_b32_e32 v41, v249
	v_mov_b32_e32 v42, v250
	v_mov_b32_e32 v43, v251
	v_mov_b32_e32 v44, v252
	v_mov_b32_e32 v45, v253
	v_mov_b32_e32 v46, v186
	v_mov_b32_e32 v47, v187
	v_mov_b32_e32 v48, v188
	v_mov_b32_e32 v49, v189
	v_mov_b32_e32 v50, v190
	v_mov_b32_e32 v51, v191
	v_mov_b32_e32 v52, v192
	v_mov_b32_e32 v53, v193
	v_mov_b32_e32 v54, v242
	v_mov_b32_e32 v55, v243
	v_mov_b32_e32 v56, v254
	v_mov_b32_e32 v57, v255
.Lg1x_join:
	s_waitcnt lgkmcnt(0)
	s_barrier
	global_load_dwordx4 v[120:123], v[106:107], off offset:256
	global_load_dwordx4 v[136:139], v[108:109], off offset:256
	global_load_dwordx4 v[140:143], v[102:103], off offset:256
	global_load_dwordx4 v[144:147], v[104:105], off offset:256
	global_load_dwordx4 v[148:151], v[110:111], off offset:256
	global_load_dwordx4 v[152:155], v[112:113], off offset:256
	global_load_dwordx4 v[156:159], v[116:117], off offset:256
	v_and_b32_e32 v3, 31, v58
	v_lshrrev_b32_e32 v2, 1, v58
	v_and_or_b32 v4, v2, s3, v3
	v_bfe_i32 v5, v58, 6, 1
	s_movk_i32 s3, 0x60
	v_and_b32_e32 v2, 16, v2
	v_and_or_b32 v3, v5, s3, v3
	v_mad_u32_u24 v115, v3, s50, v2
	v_add_u32_e32 v98, 0x12000, v115
	s_waitcnt vmcnt(13)
	ds_write_b128 v119, v[30:33]
	s_waitcnt vmcnt(12)
	ds_write_b128 v119, v[34:37] offset:9216
	s_waitcnt vmcnt(11)
	ds_write_b128 v119, v[38:41] offset:18432
	s_waitcnt vmcnt(10)
	ds_write_b128 v119, v[42:45] offset:27648
	s_waitcnt vmcnt(9)
	ds_write_b128 v119, v[46:49] offset:36864
	s_waitcnt vmcnt(8)
	ds_write_b128 v119, v[50:53] offset:46080
	s_waitcnt vmcnt(7)
	ds_write_b128 v119, v[54:57] offset:55296
	v_mad_u64_u32 v[100:101], s[10:11], v4, s50, v[2:3]
	ds_read_b128 v[18:21], v115 offset:36864
	ds_read_b128 v[162:165], v115 offset:36896
	ds_read_b128 v[22:25], v115 offset:41472
	ds_read_b128 v[166:169], v115 offset:41504
	ds_read_b128 v[26:29], v115 offset:46080
	ds_read_b128 v[170:173], v115 offset:46112
	ds_read_b128 v[2:5], v100
	ds_read_b128 v[174:177], v100 offset:32
	ds_read_b128 v[30:33], v100 offset:4608
	ds_read_b128 v[178:181], v100 offset:4640
	s_setprio 1
	s_waitcnt lgkmcnt(3)
	v_mfma_f32_32x32x16_bf16 v[82:97], v[2:5], v[18:21], 0
	v_mfma_f32_32x32x16_bf16 v[50:65], v[2:5], v[22:25], 0
	v_mfma_f32_32x32x16_bf16 v[2:17], v[2:5], v[26:29], 0
	s_waitcnt lgkmcnt(1)
	v_mfma_f32_32x32x16_bf16 v[66:81], v[30:33], v[18:21], 0
	v_mfma_f32_32x32x16_bf16 v[34:49], v[30:33], v[22:25], 0
	v_mfma_f32_32x32x16_bf16 v[18:33], v[30:33], v[26:29], 0
	s_setprio 0
	ds_read_b128 v[182:185], v115 offset:36928
	ds_read_b128 v[186:189], v115 offset:41536
	ds_read_b128 v[190:193], v115 offset:46144
	ds_read_b128 v[194:197], v100 offset:64
	ds_read_b128 v[198:201], v100 offset:4672
	s_setprio 1
	v_mfma_f32_32x32x16_bf16 v[82:97], v[174:177], v[162:165], v[82:97]
	v_mfma_f32_32x32x16_bf16 v[50:65], v[174:177], v[166:169], v[50:65]
	v_mfma_f32_32x32x16_bf16 v[2:17], v[174:177], v[170:173], v[2:17]
	s_waitcnt lgkmcnt(5)
	v_mfma_f32_32x32x16_bf16 v[66:81], v[178:181], v[162:165], v[66:81]
	v_mfma_f32_32x32x16_bf16 v[34:49], v[178:181], v[166:169], v[34:49]
	v_mfma_f32_32x32x16_bf16 v[18:33], v[178:181], v[170:173], v[18:33]
	s_setprio 0
	ds_read_b128 v[162:165], v115 offset:36960
	ds_read_b128 v[166:169], v115 offset:41568
	ds_read_b128 v[170:173], v115 offset:46176
	ds_read_b128 v[174:177], v100 offset:96
	ds_read_b128 v[178:181], v100 offset:4704
	s_setprio 1
	s_waitcnt lgkmcnt(6)
	v_mfma_f32_32x32x16_bf16 v[82:97], v[194:197], v[182:185], v[82:97]
	v_mfma_f32_32x32x16_bf16 v[50:65], v[194:197], v[186:189], v[50:65]
	v_mfma_f32_32x32x16_bf16 v[2:17], v[194:197], v[190:193], v[2:17]
	s_waitcnt lgkmcnt(5)
	v_mfma_f32_32x32x16_bf16 v[66:81], v[198:201], v[182:185], v[66:81]
	v_mfma_f32_32x32x16_bf16 v[34:49], v[198:201], v[186:189], v[34:49]
	v_mfma_f32_32x32x16_bf16 v[18:33], v[198:201], v[190:193], v[18:33]
	s_setprio 0
	s_setprio 1
	s_waitcnt lgkmcnt(1)
	v_mfma_f32_32x32x16_bf16 v[82:97], v[174:177], v[162:165], v[82:97]
	v_mfma_f32_32x32x16_bf16 v[50:65], v[174:177], v[166:169], v[50:65]
	v_mfma_f32_32x32x16_bf16 v[2:17], v[174:177], v[170:173], v[2:17]
	s_waitcnt lgkmcnt(0)
	v_mfma_f32_32x32x16_bf16 v[66:81], v[178:181], v[162:165], v[66:81]
	v_mfma_f32_32x32x16_bf16 v[34:49], v[178:181], v[166:169], v[34:49]
	v_mfma_f32_32x32x16_bf16 v[18:33], v[178:181], v[170:173], v[18:33]
	s_setprio 0
	s_barrier
	global_load_dwordx4 v[162:165], v[106:107], off offset:384
	global_load_dwordx4 v[166:169], v[108:109], off offset:384
	global_load_dwordx4 v[170:173], v[102:103], off offset:384
	global_load_dwordx4 v[174:177], v[104:105], off offset:384
	global_load_dwordx4 v[178:181], v[110:111], off offset:384
	global_load_dwordx4 v[182:185], v[112:113], off offset:384
	global_load_dwordx4 v[186:189], v[116:117], off offset:384
	s_waitcnt vmcnt(11)
	ds_write_b128 v114, v[140:143]
	ds_write_b128 v114, v[120:123] offset:9216
	ds_write_b128 v114, v[136:139] offset:18432
	s_waitcnt vmcnt(9)
	ds_write_b128 v114, v[148:151] offset:27648
	ds_write_b128 v114, v[144:147] offset:36864
	s_waitcnt vmcnt(8)
	ds_write_b128 v114, v[152:155] offset:46080
	s_waitcnt vmcnt(7)
	ds_write_b128 v114, v[156:159] offset:55296
	v_add_u32_e32 v101, 0x12000, v100
	ds_read_b128 v[120:123], v98 offset:36864
	ds_read_b128 v[136:139], v98 offset:36896
	ds_read_b128 v[140:143], v98 offset:41472
	ds_read_b128 v[144:147], v98 offset:41504
	ds_read_b128 v[148:151], v98 offset:46080
	ds_read_b128 v[152:155], v98 offset:46112
	ds_read_b128 v[156:159], v101
	ds_read_b128 v[190:193], v101 offset:32
	ds_read_b128 v[194:197], v101 offset:4608
	ds_read_b128 v[198:201], v101 offset:4640
	s_setprio 1
	s_waitcnt lgkmcnt(3)
	v_mfma_f32_32x32x16_bf16 v[82:97], v[156:159], v[120:123], v[82:97]
	v_mfma_f32_32x32x16_bf16 v[50:65], v[156:159], v[140:143], v[50:65]
	v_mfma_f32_32x32x16_bf16 v[2:17], v[156:159], v[148:151], v[2:17]
	s_waitcnt lgkmcnt(1)
	v_mfma_f32_32x32x16_bf16 v[66:81], v[194:197], v[120:123], v[66:81]
	v_mfma_f32_32x32x16_bf16 v[34:49], v[194:197], v[140:143], v[34:49]
	v_mfma_f32_32x32x16_bf16 v[18:33], v[194:197], v[148:151], v[18:33]
	s_setprio 0
	ds_read_b128 v[120:123], v98 offset:36928
	ds_read_b128 v[140:143], v98 offset:41536
	ds_read_b128 v[148:151], v98 offset:46144
	ds_read_b128 v[156:159], v101 offset:64
	ds_read_b128 v[194:197], v101 offset:4672
	s_setprio 1
	v_mfma_f32_32x32x16_bf16 v[82:97], v[190:193], v[136:139], v[82:97]
	v_mfma_f32_32x32x16_bf16 v[50:65], v[190:193], v[144:147], v[50:65]
	v_mfma_f32_32x32x16_bf16 v[2:17], v[190:193], v[152:155], v[2:17]
	s_waitcnt lgkmcnt(5)
	v_mfma_f32_32x32x16_bf16 v[66:81], v[198:201], v[136:139], v[66:81]
	v_mfma_f32_32x32x16_bf16 v[34:49], v[198:201], v[144:147], v[34:49]
	v_mfma_f32_32x32x16_bf16 v[18:33], v[198:201], v[152:155], v[18:33]
	s_setprio 0
	ds_read_b128 v[136:139], v98 offset:36960
	ds_read_b128 v[144:147], v98 offset:41568
	ds_read_b128 v[152:155], v98 offset:46176
	ds_read_b128 v[190:193], v101 offset:96
	ds_read_b128 v[198:201], v101 offset:4704
	s_setprio 1
	s_waitcnt lgkmcnt(6)
	v_mfma_f32_32x32x16_bf16 v[82:97], v[156:159], v[120:123], v[82:97]
	v_mfma_f32_32x32x16_bf16 v[50:65], v[156:159], v[140:143], v[50:65]
	v_mfma_f32_32x32x16_bf16 v[2:17], v[156:159], v[148:151], v[2:17]
	s_waitcnt lgkmcnt(5)
	v_mfma_f32_32x32x16_bf16 v[66:81], v[194:197], v[120:123], v[66:81]
	v_mfma_f32_32x32x16_bf16 v[34:49], v[194:197], v[140:143], v[34:49]
	v_mfma_f32_32x32x16_bf16 v[18:33], v[194:197], v[148:151], v[18:33]
	s_setprio 0
	s_setprio 1
	s_waitcnt lgkmcnt(1)
	v_mfma_f32_32x32x16_bf16 v[82:97], v[190:193], v[136:139], v[82:97]
	v_mfma_f32_32x32x16_bf16 v[50:65], v[190:193], v[144:147], v[50:65]
	v_mfma_f32_32x32x16_bf16 v[2:17], v[190:193], v[152:155], v[2:17]
	s_waitcnt lgkmcnt(0)
	v_mfma_f32_32x32x16_bf16 v[66:81], v[198:201], v[136:139], v[66:81]
	v_mfma_f32_32x32x16_bf16 v[34:49], v[198:201], v[144:147], v[34:49]
	v_mfma_f32_32x32x16_bf16 v[18:33], v[198:201], v[152:155], v[18:33]
	s_setprio 0
	s_barrier
	global_load_dwordx4 v[120:123], v[106:107], off offset:512
	global_load_dwordx4 v[136:139], v[108:109], off offset:512
	global_load_dwordx4 v[140:143], v[102:103], off offset:512
	global_load_dwordx4 v[144:147], v[104:105], off offset:512
	global_load_dwordx4 v[148:151], v[110:111], off offset:512
	global_load_dwordx4 v[152:155], v[112:113], off offset:512
	global_load_dwordx4 v[156:159], v[116:117], off offset:512
	s_waitcnt vmcnt(11)
	ds_write_b128 v119, v[170:173]
	ds_write_b128 v119, v[162:165] offset:9216
	ds_write_b128 v119, v[166:169] offset:18432
	s_waitcnt vmcnt(9)
	ds_write_b128 v119, v[178:181] offset:27648
	ds_write_b128 v119, v[174:177] offset:36864
	s_waitcnt vmcnt(8)
	ds_write_b128 v119, v[182:185] offset:46080
	s_waitcnt vmcnt(7)
	ds_write_b128 v119, v[186:189] offset:55296
	ds_read_b128 v[162:165], v115 offset:36864
	ds_read_b128 v[166:169], v115 offset:36896
	ds_read_b128 v[170:173], v115 offset:41472
	ds_read_b128 v[174:177], v115 offset:41504
	ds_read_b128 v[178:181], v115 offset:46080
	ds_read_b128 v[182:185], v115 offset:46112
	ds_read_b128 v[186:189], v100
	ds_read_b128 v[190:193], v100 offset:32
	ds_read_b128 v[194:197], v100 offset:4608
	ds_read_b128 v[198:201], v100 offset:4640
	s_setprio 1
	s_waitcnt lgkmcnt(3)
	v_mfma_f32_32x32x16_bf16 v[82:97], v[186:189], v[162:165], v[82:97]
	v_mfma_f32_32x32x16_bf16 v[50:65], v[186:189], v[170:173], v[50:65]
	v_mfma_f32_32x32x16_bf16 v[2:17], v[186:189], v[178:181], v[2:17]
	s_waitcnt lgkmcnt(1)
	v_mfma_f32_32x32x16_bf16 v[66:81], v[194:197], v[162:165], v[66:81]
	v_mfma_f32_32x32x16_bf16 v[34:49], v[194:197], v[170:173], v[34:49]
	v_mfma_f32_32x32x16_bf16 v[18:33], v[194:197], v[178:181], v[18:33]
	s_setprio 0
	ds_read_b128 v[162:165], v115 offset:36928
	ds_read_b128 v[170:173], v115 offset:41536
	ds_read_b128 v[178:181], v115 offset:46144
	ds_read_b128 v[186:189], v100 offset:64
	ds_read_b128 v[194:197], v100 offset:4672
	s_setprio 1
	v_mfma_f32_32x32x16_bf16 v[82:97], v[190:193], v[166:169], v[82:97]
	v_mfma_f32_32x32x16_bf16 v[50:65], v[190:193], v[174:177], v[50:65]
	v_mfma_f32_32x32x16_bf16 v[2:17], v[190:193], v[182:185], v[2:17]
	s_waitcnt lgkmcnt(5)
	v_mfma_f32_32x32x16_bf16 v[66:81], v[198:201], v[166:169], v[66:81]
	v_mfma_f32_32x32x16_bf16 v[34:49], v[198:201], v[174:177], v[34:49]
	v_mfma_f32_32x32x16_bf16 v[18:33], v[198:201], v[182:185], v[18:33]
	s_setprio 0
	ds_read_b128 v[166:169], v115 offset:36960
	ds_read_b128 v[174:177], v115 offset:41568
	ds_read_b128 v[182:185], v115 offset:46176
	ds_read_b128 v[190:193], v100 offset:96
	ds_read_b128 v[198:201], v100 offset:4704
	s_setprio 1
	s_waitcnt lgkmcnt(6)
	v_mfma_f32_32x32x16_bf16 v[82:97], v[186:189], v[162:165], v[82:97]
	v_mfma_f32_32x32x16_bf16 v[50:65], v[186:189], v[170:173], v[50:65]
	v_mfma_f32_32x32x16_bf16 v[2:17], v[186:189], v[178:181], v[2:17]
	s_waitcnt lgkmcnt(5)
	v_mfma_f32_32x32x16_bf16 v[66:81], v[194:197], v[162:165], v[66:81]
	v_mfma_f32_32x32x16_bf16 v[34:49], v[194:197], v[170:173], v[34:49]
	v_mfma_f32_32x32x16_bf16 v[18:33], v[194:197], v[178:181], v[18:33]
	s_setprio 0
	s_setprio 1
	s_waitcnt lgkmcnt(1)
	v_mfma_f32_32x32x16_bf16 v[82:97], v[190:193], v[166:169], v[82:97]
	v_mfma_f32_32x32x16_bf16 v[50:65], v[190:193], v[174:177], v[50:65]
	v_mfma_f32_32x32x16_bf16 v[2:17], v[190:193], v[182:185], v[2:17]
	s_waitcnt lgkmcnt(0)
	v_mfma_f32_32x32x16_bf16 v[66:81], v[198:201], v[166:169], v[66:81]
	v_mfma_f32_32x32x16_bf16 v[34:49], v[198:201], v[174:177], v[34:49]
	v_mfma_f32_32x32x16_bf16 v[18:33], v[198:201], v[182:185], v[18:33]
	s_setprio 0
	s_barrier
	global_load_dwordx4 v[162:165], v[106:107], off offset:640
	global_load_dwordx4 v[166:169], v[108:109], off offset:640
	global_load_dwordx4 v[170:173], v[102:103], off offset:640
	global_load_dwordx4 v[174:177], v[104:105], off offset:640
	global_load_dwordx4 v[178:181], v[110:111], off offset:640
	global_load_dwordx4 v[182:185], v[112:113], off offset:640
	global_load_dwordx4 v[186:189], v[116:117], off offset:640
	s_waitcnt vmcnt(11)
	ds_write_b128 v114, v[140:143]
	ds_write_b128 v114, v[120:123] offset:9216
	ds_write_b128 v114, v[136:139] offset:18432
	s_waitcnt vmcnt(9)
	ds_write_b128 v114, v[148:151] offset:27648
	ds_write_b128 v114, v[144:147] offset:36864
	s_waitcnt vmcnt(8)
	ds_write_b128 v114, v[152:155] offset:46080
	s_waitcnt vmcnt(7)
	ds_write_b128 v114, v[156:159] offset:55296
	ds_read_b128 v[120:123], v98 offset:36864
	ds_read_b128 v[136:139], v98 offset:36896
	ds_read_b128 v[140:143], v98 offset:41472
	ds_read_b128 v[144:147], v98 offset:41504
	ds_read_b128 v[148:151], v98 offset:46080
	ds_read_b128 v[152:155], v98 offset:46112
	ds_read_b128 v[156:159], v101
	ds_read_b128 v[190:193], v101 offset:32
	ds_read_b128 v[194:197], v101 offset:4608
	ds_read_b128 v[198:201], v101 offset:4640
	s_setprio 1
	s_waitcnt lgkmcnt(3)
	v_mfma_f32_32x32x16_bf16 v[82:97], v[156:159], v[120:123], v[82:97]
	v_mfma_f32_32x32x16_bf16 v[50:65], v[156:159], v[140:143], v[50:65]
	v_mfma_f32_32x32x16_bf16 v[2:17], v[156:159], v[148:151], v[2:17]
	s_waitcnt lgkmcnt(1)
	v_mfma_f32_32x32x16_bf16 v[66:81], v[194:197], v[120:123], v[66:81]
	v_mfma_f32_32x32x16_bf16 v[34:49], v[194:197], v[140:143], v[34:49]
	v_mfma_f32_32x32x16_bf16 v[18:33], v[194:197], v[148:151], v[18:33]
	s_setprio 0
	ds_read_b128 v[120:123], v98 offset:36928
	ds_read_b128 v[140:143], v98 offset:41536
	ds_read_b128 v[148:151], v98 offset:46144
	ds_read_b128 v[156:159], v101 offset:64
	ds_read_b128 v[194:197], v101 offset:4672
	s_setprio 1
	v_mfma_f32_32x32x16_bf16 v[82:97], v[190:193], v[136:139], v[82:97]
	v_mfma_f32_32x32x16_bf16 v[50:65], v[190:193], v[144:147], v[50:65]
	v_mfma_f32_32x32x16_bf16 v[2:17], v[190:193], v[152:155], v[2:17]
	s_waitcnt lgkmcnt(5)
	v_mfma_f32_32x32x16_bf16 v[66:81], v[198:201], v[136:139], v[66:81]
	v_mfma_f32_32x32x16_bf16 v[34:49], v[198:201], v[144:147], v[34:49]
	v_mfma_f32_32x32x16_bf16 v[18:33], v[198:201], v[152:155], v[18:33]
	s_setprio 0
	ds_read_b128 v[136:139], v98 offset:36960
	ds_read_b128 v[144:147], v98 offset:41568
	ds_read_b128 v[152:155], v98 offset:46176
	ds_read_b128 v[190:193], v101 offset:96
	ds_read_b128 v[198:201], v101 offset:4704
	s_setprio 1
	s_waitcnt lgkmcnt(6)
	v_mfma_f32_32x32x16_bf16 v[82:97], v[156:159], v[120:123], v[82:97]
	v_mfma_f32_32x32x16_bf16 v[50:65], v[156:159], v[140:143], v[50:65]
	v_mfma_f32_32x32x16_bf16 v[2:17], v[156:159], v[148:151], v[2:17]
	s_waitcnt lgkmcnt(5)
	v_mfma_f32_32x32x16_bf16 v[66:81], v[194:197], v[120:123], v[66:81]
	v_mfma_f32_32x32x16_bf16 v[34:49], v[194:197], v[140:143], v[34:49]
	v_mfma_f32_32x32x16_bf16 v[18:33], v[194:197], v[148:151], v[18:33]
	s_setprio 0
	s_setprio 1
	s_waitcnt lgkmcnt(1)
	v_mfma_f32_32x32x16_bf16 v[82:97], v[190:193], v[136:139], v[82:97]
	v_mfma_f32_32x32x16_bf16 v[50:65], v[190:193], v[144:147], v[50:65]
	v_mfma_f32_32x32x16_bf16 v[2:17], v[190:193], v[152:155], v[2:17]
	s_waitcnt lgkmcnt(0)
	v_mfma_f32_32x32x16_bf16 v[66:81], v[198:201], v[136:139], v[66:81]
	v_mfma_f32_32x32x16_bf16 v[34:49], v[198:201], v[144:147], v[34:49]
	v_mfma_f32_32x32x16_bf16 v[18:33], v[198:201], v[152:155], v[18:33]
	s_setprio 0
	s_barrier
	global_load_dwordx4 v[120:123], v[106:107], off offset:768
	global_load_dwordx4 v[136:139], v[108:109], off offset:768
	global_load_dwordx4 v[140:143], v[102:103], off offset:768
	global_load_dwordx4 v[144:147], v[104:105], off offset:768
	global_load_dwordx4 v[148:151], v[110:111], off offset:768
	global_load_dwordx4 v[152:155], v[112:113], off offset:768
	global_load_dwordx4 v[156:159], v[116:117], off offset:768
	s_waitcnt vmcnt(11)
	ds_write_b128 v119, v[170:173]
	ds_write_b128 v119, v[162:165] offset:9216
	ds_write_b128 v119, v[166:169] offset:18432
	s_waitcnt vmcnt(9)
	ds_write_b128 v119, v[178:181] offset:27648
	ds_write_b128 v119, v[174:177] offset:36864
	s_waitcnt vmcnt(8)
	ds_write_b128 v119, v[182:185] offset:46080
	s_waitcnt vmcnt(7)
	ds_write_b128 v119, v[186:189] offset:55296
	ds_read_b128 v[162:165], v115 offset:36864
	ds_read_b128 v[166:169], v115 offset:36896
	ds_read_b128 v[170:173], v115 offset:41472
	ds_read_b128 v[174:177], v115 offset:41504
	ds_read_b128 v[178:181], v115 offset:46080
	ds_read_b128 v[182:185], v115 offset:46112
	ds_read_b128 v[186:189], v100
	ds_read_b128 v[190:193], v100 offset:32
	ds_read_b128 v[194:197], v100 offset:4608
	ds_read_b128 v[198:201], v100 offset:4640
	s_setprio 1
	s_waitcnt lgkmcnt(3)
	v_mfma_f32_32x32x16_bf16 v[82:97], v[186:189], v[162:165], v[82:97]
	v_mfma_f32_32x32x16_bf16 v[50:65], v[186:189], v[170:173], v[50:65]
	v_mfma_f32_32x32x16_bf16 v[2:17], v[186:189], v[178:181], v[2:17]
	s_waitcnt lgkmcnt(1)
	v_mfma_f32_32x32x16_bf16 v[66:81], v[194:197], v[162:165], v[66:81]
	v_mfma_f32_32x32x16_bf16 v[34:49], v[194:197], v[170:173], v[34:49]
	v_mfma_f32_32x32x16_bf16 v[18:33], v[194:197], v[178:181], v[18:33]
	s_setprio 0
	ds_read_b128 v[162:165], v115 offset:36928
	ds_read_b128 v[170:173], v115 offset:41536
	ds_read_b128 v[178:181], v115 offset:46144
	ds_read_b128 v[186:189], v100 offset:64
	ds_read_b128 v[194:197], v100 offset:4672
	s_setprio 1
	v_mfma_f32_32x32x16_bf16 v[82:97], v[190:193], v[166:169], v[82:97]
	v_mfma_f32_32x32x16_bf16 v[50:65], v[190:193], v[174:177], v[50:65]
	v_mfma_f32_32x32x16_bf16 v[2:17], v[190:193], v[182:185], v[2:17]
	s_waitcnt lgkmcnt(5)
	v_mfma_f32_32x32x16_bf16 v[66:81], v[198:201], v[166:169], v[66:81]
	v_mfma_f32_32x32x16_bf16 v[34:49], v[198:201], v[174:177], v[34:49]
	v_mfma_f32_32x32x16_bf16 v[18:33], v[198:201], v[182:185], v[18:33]
	s_setprio 0
	ds_read_b128 v[166:169], v115 offset:36960
	ds_read_b128 v[174:177], v115 offset:41568
	ds_read_b128 v[182:185], v115 offset:46176
	ds_read_b128 v[190:193], v100 offset:96
	ds_read_b128 v[198:201], v100 offset:4704
	s_setprio 1
	s_waitcnt lgkmcnt(6)
	v_mfma_f32_32x32x16_bf16 v[82:97], v[186:189], v[162:165], v[82:97]
	v_mfma_f32_32x32x16_bf16 v[50:65], v[186:189], v[170:173], v[50:65]
	v_mfma_f32_32x32x16_bf16 v[2:17], v[186:189], v[178:181], v[2:17]
	s_waitcnt lgkmcnt(5)
	v_mfma_f32_32x32x16_bf16 v[66:81], v[194:197], v[162:165], v[66:81]
	v_mfma_f32_32x32x16_bf16 v[34:49], v[194:197], v[170:173], v[34:49]
	v_mfma_f32_32x32x16_bf16 v[18:33], v[194:197], v[178:181], v[18:33]
	s_setprio 0
	s_setprio 1
	s_waitcnt lgkmcnt(1)
	v_mfma_f32_32x32x16_bf16 v[82:97], v[190:193], v[166:169], v[82:97]
	v_mfma_f32_32x32x16_bf16 v[50:65], v[190:193], v[174:177], v[50:65]
	v_mfma_f32_32x32x16_bf16 v[2:17], v[190:193], v[182:185], v[2:17]
	s_waitcnt lgkmcnt(0)
	v_mfma_f32_32x32x16_bf16 v[66:81], v[198:201], v[166:169], v[66:81]
	v_mfma_f32_32x32x16_bf16 v[34:49], v[198:201], v[174:177], v[34:49]
	v_mfma_f32_32x32x16_bf16 v[18:33], v[198:201], v[182:185], v[18:33]
	s_setprio 0
	s_barrier
	global_load_dwordx4 v[162:165], v[106:107], off offset:896
	global_load_dwordx4 v[166:169], v[108:109], off offset:896
	global_load_dwordx4 v[170:173], v[102:103], off offset:896
	global_load_dwordx4 v[174:177], v[104:105], off offset:896
	global_load_dwordx4 v[178:181], v[110:111], off offset:896
	global_load_dwordx4 v[182:185], v[112:113], off offset:896
	global_load_dwordx4 v[186:189], v[116:117], off offset:896
	s_waitcnt vmcnt(11)
	ds_write_b128 v114, v[140:143]
	ds_write_b128 v114, v[120:123] offset:9216
	ds_write_b128 v114, v[136:139] offset:18432
	s_waitcnt vmcnt(9)
	ds_write_b128 v114, v[148:151] offset:27648
	ds_write_b128 v114, v[144:147] offset:36864
	s_waitcnt vmcnt(8)
	ds_write_b128 v114, v[152:155] offset:46080
	s_waitcnt vmcnt(7)
	ds_write_b128 v114, v[156:159] offset:55296
	ds_read_b128 v[120:123], v98 offset:36864
	ds_read_b128 v[136:139], v98 offset:36896
	ds_read_b128 v[140:143], v98 offset:41472
	ds_read_b128 v[144:147], v98 offset:41504
	ds_read_b128 v[148:151], v98 offset:46080
	ds_read_b128 v[152:155], v98 offset:46112
	ds_read_b128 v[156:159], v101
	ds_read_b128 v[190:193], v101 offset:32
	ds_read_b128 v[194:197], v101 offset:4608
	ds_read_b128 v[198:201], v101 offset:4640
	s_setprio 1
	s_waitcnt lgkmcnt(3)
	v_mfma_f32_32x32x16_bf16 v[82:97], v[156:159], v[120:123], v[82:97]
	v_mfma_f32_32x32x16_bf16 v[50:65], v[156:159], v[140:143], v[50:65]
	v_mfma_f32_32x32x16_bf16 v[2:17], v[156:159], v[148:151], v[2:17]
	s_waitcnt lgkmcnt(1)
	v_mfma_f32_32x32x16_bf16 v[66:81], v[194:197], v[120:123], v[66:81]
	v_mfma_f32_32x32x16_bf16 v[34:49], v[194:197], v[140:143], v[34:49]
	v_mfma_f32_32x32x16_bf16 v[18:33], v[194:197], v[148:151], v[18:33]
	s_setprio 0
	ds_read_b128 v[120:123], v98 offset:36928
	ds_read_b128 v[140:143], v98 offset:41536
	ds_read_b128 v[148:151], v98 offset:46144
	ds_read_b128 v[156:159], v101 offset:64
	ds_read_b128 v[194:197], v101 offset:4672
	s_setprio 1
	v_mfma_f32_32x32x16_bf16 v[82:97], v[190:193], v[136:139], v[82:97]
	v_mfma_f32_32x32x16_bf16 v[50:65], v[190:193], v[144:147], v[50:65]
	v_mfma_f32_32x32x16_bf16 v[2:17], v[190:193], v[152:155], v[2:17]
	s_waitcnt lgkmcnt(5)
	v_mfma_f32_32x32x16_bf16 v[66:81], v[198:201], v[136:139], v[66:81]
	v_mfma_f32_32x32x16_bf16 v[34:49], v[198:201], v[144:147], v[34:49]
	v_mfma_f32_32x32x16_bf16 v[18:33], v[198:201], v[152:155], v[18:33]
	s_setprio 0
	ds_read_b128 v[136:139], v98 offset:36960
	ds_read_b128 v[144:147], v98 offset:41568
	ds_read_b128 v[152:155], v98 offset:46176
	ds_read_b128 v[190:193], v101 offset:96
	ds_read_b128 v[198:201], v101 offset:4704
	s_setprio 1
	s_waitcnt lgkmcnt(6)
	v_mfma_f32_32x32x16_bf16 v[82:97], v[156:159], v[120:123], v[82:97]
	v_mfma_f32_32x32x16_bf16 v[50:65], v[156:159], v[140:143], v[50:65]
	v_mfma_f32_32x32x16_bf16 v[2:17], v[156:159], v[148:151], v[2:17]
	s_waitcnt lgkmcnt(5)
	v_mfma_f32_32x32x16_bf16 v[66:81], v[194:197], v[120:123], v[66:81]
	v_mfma_f32_32x32x16_bf16 v[34:49], v[194:197], v[140:143], v[34:49]
	v_mfma_f32_32x32x16_bf16 v[18:33], v[194:197], v[148:151], v[18:33]
	s_setprio 0
	s_setprio 1
	s_waitcnt lgkmcnt(1)
	v_mfma_f32_32x32x16_bf16 v[82:97], v[190:193], v[136:139], v[82:97]
	v_mfma_f32_32x32x16_bf16 v[50:65], v[190:193], v[144:147], v[50:65]
	v_mfma_f32_32x32x16_bf16 v[2:17], v[190:193], v[152:155], v[2:17]
	s_waitcnt lgkmcnt(0)
	v_mfma_f32_32x32x16_bf16 v[66:81], v[198:201], v[136:139], v[66:81]
	v_mfma_f32_32x32x16_bf16 v[34:49], v[198:201], v[144:147], v[34:49]
	v_mfma_f32_32x32x16_bf16 v[18:33], v[198:201], v[152:155], v[18:33]
	s_setprio 0
	s_barrier
	global_load_dwordx4 v[120:123], v[106:107], off offset:1024
	global_load_dwordx4 v[136:139], v[108:109], off offset:1024
	global_load_dwordx4 v[140:143], v[102:103], off offset:1024
	global_load_dwordx4 v[144:147], v[104:105], off offset:1024
	global_load_dwordx4 v[148:151], v[110:111], off offset:1024
	global_load_dwordx4 v[152:155], v[112:113], off offset:1024
	global_load_dwordx4 v[156:159], v[116:117], off offset:1024
	s_waitcnt vmcnt(11)
	ds_write_b128 v119, v[170:173]
	ds_write_b128 v119, v[162:165] offset:9216
	ds_write_b128 v119, v[166:169] offset:18432
	s_waitcnt vmcnt(9)
	ds_write_b128 v119, v[178:181] offset:27648
	ds_write_b128 v119, v[174:177] offset:36864
	s_waitcnt vmcnt(8)
	ds_write_b128 v119, v[182:185] offset:46080
	s_waitcnt vmcnt(7)
	ds_write_b128 v119, v[186:189] offset:55296
	ds_read_b128 v[162:165], v115 offset:36864
	ds_read_b128 v[166:169], v115 offset:36896
	ds_read_b128 v[170:173], v115 offset:41472
	ds_read_b128 v[174:177], v115 offset:41504
	ds_read_b128 v[178:181], v115 offset:46080
	ds_read_b128 v[182:185], v115 offset:46112
	ds_read_b128 v[186:189], v100
	ds_read_b128 v[190:193], v100 offset:32
	ds_read_b128 v[194:197], v100 offset:4608
	ds_read_b128 v[198:201], v100 offset:4640
	s_setprio 1
	s_waitcnt lgkmcnt(3)
	v_mfma_f32_32x32x16_bf16 v[82:97], v[186:189], v[162:165], v[82:97]
	v_mfma_f32_32x32x16_bf16 v[50:65], v[186:189], v[170:173], v[50:65]
	v_mfma_f32_32x32x16_bf16 v[2:17], v[186:189], v[178:181], v[2:17]
	s_waitcnt lgkmcnt(1)
	v_mfma_f32_32x32x16_bf16 v[66:81], v[194:197], v[162:165], v[66:81]
	v_mfma_f32_32x32x16_bf16 v[34:49], v[194:197], v[170:173], v[34:49]
	v_mfma_f32_32x32x16_bf16 v[18:33], v[194:197], v[178:181], v[18:33]
	s_setprio 0
	ds_read_b128 v[162:165], v115 offset:36928
	ds_read_b128 v[170:173], v115 offset:41536
	ds_read_b128 v[178:181], v115 offset:46144
	ds_read_b128 v[186:189], v100 offset:64
	ds_read_b128 v[194:197], v100 offset:4672
	s_setprio 1
	v_mfma_f32_32x32x16_bf16 v[82:97], v[190:193], v[166:169], v[82:97]
	v_mfma_f32_32x32x16_bf16 v[50:65], v[190:193], v[174:177], v[50:65]
	v_mfma_f32_32x32x16_bf16 v[2:17], v[190:193], v[182:185], v[2:17]
	s_waitcnt lgkmcnt(5)
	v_mfma_f32_32x32x16_bf16 v[66:81], v[198:201], v[166:169], v[66:81]
	v_mfma_f32_32x32x16_bf16 v[34:49], v[198:201], v[174:177], v[34:49]
	v_mfma_f32_32x32x16_bf16 v[18:33], v[198:201], v[182:185], v[18:33]
	s_setprio 0
	ds_read_b128 v[166:169], v115 offset:36960
	ds_read_b128 v[174:177], v115 offset:41568
	ds_read_b128 v[182:185], v115 offset:46176
	ds_read_b128 v[190:193], v100 offset:96
	ds_read_b128 v[198:201], v100 offset:4704
	s_setprio 1
	s_waitcnt lgkmcnt(6)
	v_mfma_f32_32x32x16_bf16 v[82:97], v[186:189], v[162:165], v[82:97]
	v_mfma_f32_32x32x16_bf16 v[50:65], v[186:189], v[170:173], v[50:65]
	v_mfma_f32_32x32x16_bf16 v[2:17], v[186:189], v[178:181], v[2:17]
	s_waitcnt lgkmcnt(5)
	v_mfma_f32_32x32x16_bf16 v[66:81], v[194:197], v[162:165], v[66:81]
	v_mfma_f32_32x32x16_bf16 v[34:49], v[194:197], v[170:173], v[34:49]
	v_mfma_f32_32x32x16_bf16 v[18:33], v[194:197], v[178:181], v[18:33]
	s_setprio 0
	s_setprio 1
	s_waitcnt lgkmcnt(1)
	v_mfma_f32_32x32x16_bf16 v[82:97], v[190:193], v[166:169], v[82:97]
	v_mfma_f32_32x32x16_bf16 v[50:65], v[190:193], v[174:177], v[50:65]
	v_mfma_f32_32x32x16_bf16 v[2:17], v[190:193], v[182:185], v[2:17]
	s_waitcnt lgkmcnt(0)
	v_mfma_f32_32x32x16_bf16 v[66:81], v[198:201], v[166:169], v[66:81]
	v_mfma_f32_32x32x16_bf16 v[34:49], v[198:201], v[174:177], v[34:49]
	v_mfma_f32_32x32x16_bf16 v[18:33], v[198:201], v[182:185], v[18:33]
	s_setprio 0
	s_barrier
	global_load_dwordx4 v[162:165], v[106:107], off offset:1152
	global_load_dwordx4 v[166:169], v[108:109], off offset:1152
	global_load_dwordx4 v[170:173], v[102:103], off offset:1152
	global_load_dwordx4 v[174:177], v[104:105], off offset:1152
	global_load_dwordx4 v[178:181], v[110:111], off offset:1152
	global_load_dwordx4 v[182:185], v[112:113], off offset:1152
	global_load_dwordx4 v[186:189], v[116:117], off offset:1152
	s_waitcnt vmcnt(11)
	ds_write_b128 v114, v[140:143]
	ds_write_b128 v114, v[120:123] offset:9216
	ds_write_b128 v114, v[136:139] offset:18432
	s_waitcnt vmcnt(9)
	ds_write_b128 v114, v[148:151] offset:27648
	ds_write_b128 v114, v[144:147] offset:36864
	s_waitcnt vmcnt(8)
	ds_write_b128 v114, v[152:155] offset:46080
	s_waitcnt vmcnt(7)
	ds_write_b128 v114, v[156:159] offset:55296
	ds_read_b128 v[120:123], v98 offset:36864
	ds_read_b128 v[136:139], v98 offset:36896
	ds_read_b128 v[140:143], v98 offset:41472
	ds_read_b128 v[144:147], v98 offset:41504
	ds_read_b128 v[148:151], v98 offset:46080
	ds_read_b128 v[152:155], v98 offset:46112
	ds_read_b128 v[156:159], v101
	ds_read_b128 v[190:193], v101 offset:32
	ds_read_b128 v[194:197], v101 offset:4608
	ds_read_b128 v[198:201], v101 offset:4640
	s_setprio 1
	s_waitcnt lgkmcnt(3)
	v_mfma_f32_32x32x16_bf16 v[82:97], v[156:159], v[120:123], v[82:97]
	v_mfma_f32_32x32x16_bf16 v[50:65], v[156:159], v[140:143], v[50:65]
	v_mfma_f32_32x32x16_bf16 v[2:17], v[156:159], v[148:151], v[2:17]
	s_waitcnt lgkmcnt(1)
	v_mfma_f32_32x32x16_bf16 v[66:81], v[194:197], v[120:123], v[66:81]
	v_mfma_f32_32x32x16_bf16 v[34:49], v[194:197], v[140:143], v[34:49]
	v_mfma_f32_32x32x16_bf16 v[18:33], v[194:197], v[148:151], v[18:33]
	s_setprio 0
	ds_read_b128 v[120:123], v98 offset:36928
	ds_read_b128 v[140:143], v98 offset:41536
	ds_read_b128 v[148:151], v98 offset:46144
	ds_read_b128 v[156:159], v101 offset:64
	ds_read_b128 v[194:197], v101 offset:4672
	s_setprio 1
	v_mfma_f32_32x32x16_bf16 v[82:97], v[190:193], v[136:139], v[82:97]
	v_mfma_f32_32x32x16_bf16 v[50:65], v[190:193], v[144:147], v[50:65]
	v_mfma_f32_32x32x16_bf16 v[2:17], v[190:193], v[152:155], v[2:17]
	s_waitcnt lgkmcnt(5)
	v_mfma_f32_32x32x16_bf16 v[66:81], v[198:201], v[136:139], v[66:81]
	v_mfma_f32_32x32x16_bf16 v[34:49], v[198:201], v[144:147], v[34:49]
	v_mfma_f32_32x32x16_bf16 v[18:33], v[198:201], v[152:155], v[18:33]
	s_setprio 0
	ds_read_b128 v[136:139], v98 offset:36960
	ds_read_b128 v[144:147], v98 offset:41568
	ds_read_b128 v[152:155], v98 offset:46176
	ds_read_b128 v[190:193], v101 offset:96
	ds_read_b128 v[198:201], v101 offset:4704
	s_setprio 1
	s_waitcnt lgkmcnt(6)
	v_mfma_f32_32x32x16_bf16 v[82:97], v[156:159], v[120:123], v[82:97]
	v_mfma_f32_32x32x16_bf16 v[50:65], v[156:159], v[140:143], v[50:65]
	v_mfma_f32_32x32x16_bf16 v[2:17], v[156:159], v[148:151], v[2:17]
	s_waitcnt lgkmcnt(5)
	v_mfma_f32_32x32x16_bf16 v[66:81], v[194:197], v[120:123], v[66:81]
	v_mfma_f32_32x32x16_bf16 v[34:49], v[194:197], v[140:143], v[34:49]
	v_mfma_f32_32x32x16_bf16 v[18:33], v[194:197], v[148:151], v[18:33]
	s_setprio 0
	s_setprio 1
	s_waitcnt lgkmcnt(1)
	v_mfma_f32_32x32x16_bf16 v[82:97], v[190:193], v[136:139], v[82:97]
	v_mfma_f32_32x32x16_bf16 v[50:65], v[190:193], v[144:147], v[50:65]
	v_mfma_f32_32x32x16_bf16 v[2:17], v[190:193], v[152:155], v[2:17]
	s_waitcnt lgkmcnt(0)
	v_mfma_f32_32x32x16_bf16 v[66:81], v[198:201], v[136:139], v[66:81]
	v_mfma_f32_32x32x16_bf16 v[34:49], v[198:201], v[144:147], v[34:49]
	v_mfma_f32_32x32x16_bf16 v[18:33], v[198:201], v[152:155], v[18:33]
	s_setprio 0
	s_barrier
	global_load_dwordx4 v[120:123], v[106:107], off offset:1280
	global_load_dwordx4 v[136:139], v[108:109], off offset:1280
	global_load_dwordx4 v[140:143], v[102:103], off offset:1280
	global_load_dwordx4 v[144:147], v[104:105], off offset:1280
	global_load_dwordx4 v[148:151], v[110:111], off offset:1280
	global_load_dwordx4 v[152:155], v[112:113], off offset:1280
	global_load_dwordx4 v[156:159], v[116:117], off offset:1280
	s_waitcnt vmcnt(11)
	ds_write_b128 v119, v[170:173]
	ds_write_b128 v119, v[162:165] offset:9216
	ds_write_b128 v119, v[166:169] offset:18432
	s_waitcnt vmcnt(9)
	ds_write_b128 v119, v[178:181] offset:27648
	ds_write_b128 v119, v[174:177] offset:36864
	s_waitcnt vmcnt(8)
	ds_write_b128 v119, v[182:185] offset:46080
	s_waitcnt vmcnt(7)
	ds_write_b128 v119, v[186:189] offset:55296
	ds_read_b128 v[162:165], v115 offset:36864
	ds_read_b128 v[166:169], v115 offset:36896
	ds_read_b128 v[170:173], v115 offset:41472
	ds_read_b128 v[174:177], v115 offset:41504
	ds_read_b128 v[178:181], v115 offset:46080
	ds_read_b128 v[182:185], v115 offset:46112
	ds_read_b128 v[186:189], v100
	ds_read_b128 v[190:193], v100 offset:32
	ds_read_b128 v[194:197], v100 offset:4608
	ds_read_b128 v[198:201], v100 offset:4640
	s_setprio 1
	s_waitcnt lgkmcnt(3)
	v_mfma_f32_32x32x16_bf16 v[82:97], v[186:189], v[162:165], v[82:97]
	v_mfma_f32_32x32x16_bf16 v[50:65], v[186:189], v[170:173], v[50:65]
	v_mfma_f32_32x32x16_bf16 v[2:17], v[186:189], v[178:181], v[2:17]
	s_waitcnt lgkmcnt(1)
	v_mfma_f32_32x32x16_bf16 v[66:81], v[194:197], v[162:165], v[66:81]
	v_mfma_f32_32x32x16_bf16 v[34:49], v[194:197], v[170:173], v[34:49]
	v_mfma_f32_32x32x16_bf16 v[18:33], v[194:197], v[178:181], v[18:33]
	s_setprio 0
	ds_read_b128 v[162:165], v115 offset:36928
	ds_read_b128 v[170:173], v115 offset:41536
	ds_read_b128 v[178:181], v115 offset:46144
	ds_read_b128 v[186:189], v100 offset:64
	ds_read_b128 v[194:197], v100 offset:4672
	s_setprio 1
	v_mfma_f32_32x32x16_bf16 v[82:97], v[190:193], v[166:169], v[82:97]
	v_mfma_f32_32x32x16_bf16 v[50:65], v[190:193], v[174:177], v[50:65]
	v_mfma_f32_32x32x16_bf16 v[2:17], v[190:193], v[182:185], v[2:17]
	s_waitcnt lgkmcnt(5)
	v_mfma_f32_32x32x16_bf16 v[66:81], v[198:201], v[166:169], v[66:81]
	v_mfma_f32_32x32x16_bf16 v[34:49], v[198:201], v[174:177], v[34:49]
	v_mfma_f32_32x32x16_bf16 v[18:33], v[198:201], v[182:185], v[18:33]
	s_setprio 0
	ds_read_b128 v[166:169], v115 offset:36960
	ds_read_b128 v[174:177], v115 offset:41568
	ds_read_b128 v[182:185], v115 offset:46176
	ds_read_b128 v[190:193], v100 offset:96
	ds_read_b128 v[198:201], v100 offset:4704
	s_setprio 1
	s_waitcnt lgkmcnt(6)
	v_mfma_f32_32x32x16_bf16 v[82:97], v[186:189], v[162:165], v[82:97]
	v_mfma_f32_32x32x16_bf16 v[50:65], v[186:189], v[170:173], v[50:65]
	v_mfma_f32_32x32x16_bf16 v[2:17], v[186:189], v[178:181], v[2:17]
	s_waitcnt lgkmcnt(5)
	v_mfma_f32_32x32x16_bf16 v[66:81], v[194:197], v[162:165], v[66:81]
	v_mfma_f32_32x32x16_bf16 v[34:49], v[194:197], v[170:173], v[34:49]
	v_mfma_f32_32x32x16_bf16 v[18:33], v[194:197], v[178:181], v[18:33]
	s_setprio 0
	s_setprio 1
	s_waitcnt lgkmcnt(1)
	v_mfma_f32_32x32x16_bf16 v[82:97], v[190:193], v[166:169], v[82:97]
	v_mfma_f32_32x32x16_bf16 v[50:65], v[190:193], v[174:177], v[50:65]
	v_mfma_f32_32x32x16_bf16 v[2:17], v[190:193], v[182:185], v[2:17]
	s_waitcnt lgkmcnt(0)
	v_mfma_f32_32x32x16_bf16 v[66:81], v[198:201], v[166:169], v[66:81]
	v_mfma_f32_32x32x16_bf16 v[34:49], v[198:201], v[174:177], v[34:49]
	v_mfma_f32_32x32x16_bf16 v[18:33], v[198:201], v[182:185], v[18:33]
	s_setprio 0
	s_barrier
	global_load_dwordx4 v[162:165], v[106:107], off offset:1408
	global_load_dwordx4 v[166:169], v[108:109], off offset:1408
	global_load_dwordx4 v[170:173], v[102:103], off offset:1408
	global_load_dwordx4 v[174:177], v[104:105], off offset:1408
	global_load_dwordx4 v[178:181], v[110:111], off offset:1408
	global_load_dwordx4 v[182:185], v[112:113], off offset:1408
	global_load_dwordx4 v[186:189], v[116:117], off offset:1408
	s_waitcnt vmcnt(11)
	ds_write_b128 v114, v[140:143]
	ds_write_b128 v114, v[120:123] offset:9216
	ds_write_b128 v114, v[136:139] offset:18432
	s_waitcnt vmcnt(9)
	ds_write_b128 v114, v[148:151] offset:27648
	ds_write_b128 v114, v[144:147] offset:36864
	s_waitcnt vmcnt(8)
	ds_write_b128 v114, v[152:155] offset:46080
	s_waitcnt vmcnt(7)
	ds_write_b128 v114, v[156:159] offset:55296
	ds_read_b128 v[120:123], v98 offset:36864
	ds_read_b128 v[136:139], v98 offset:36896
	ds_read_b128 v[140:143], v98 offset:41472
	ds_read_b128 v[144:147], v98 offset:41504
	ds_read_b128 v[148:151], v98 offset:46080
	ds_read_b128 v[152:155], v98 offset:46112
	ds_read_b128 v[156:159], v101
	ds_read_b128 v[190:193], v101 offset:32
	ds_read_b128 v[194:197], v101 offset:4608
	ds_read_b128 v[198:201], v101 offset:4640
	s_setprio 1
	s_waitcnt lgkmcnt(3)
	v_mfma_f32_32x32x16_bf16 v[82:97], v[156:159], v[120:123], v[82:97]
	v_mfma_f32_32x32x16_bf16 v[50:65], v[156:159], v[140:143], v[50:65]
	v_mfma_f32_32x32x16_bf16 v[2:17], v[156:159], v[148:151], v[2:17]
	s_waitcnt lgkmcnt(1)
	v_mfma_f32_32x32x16_bf16 v[66:81], v[194:197], v[120:123], v[66:81]
	v_mfma_f32_32x32x16_bf16 v[34:49], v[194:197], v[140:143], v[34:49]
	v_mfma_f32_32x32x16_bf16 v[18:33], v[194:197], v[148:151], v[18:33]
	s_setprio 0
	ds_read_b128 v[120:123], v98 offset:36928
	ds_read_b128 v[140:143], v98 offset:41536
	ds_read_b128 v[148:151], v98 offset:46144
	ds_read_b128 v[156:159], v101 offset:64
	ds_read_b128 v[194:197], v101 offset:4672
	s_setprio 1
	v_mfma_f32_32x32x16_bf16 v[82:97], v[190:193], v[136:139], v[82:97]
	v_mfma_f32_32x32x16_bf16 v[50:65], v[190:193], v[144:147], v[50:65]
	v_mfma_f32_32x32x16_bf16 v[2:17], v[190:193], v[152:155], v[2:17]
	s_waitcnt lgkmcnt(5)
	v_mfma_f32_32x32x16_bf16 v[66:81], v[198:201], v[136:139], v[66:81]
	v_mfma_f32_32x32x16_bf16 v[34:49], v[198:201], v[144:147], v[34:49]
	v_mfma_f32_32x32x16_bf16 v[18:33], v[198:201], v[152:155], v[18:33]
	s_setprio 0
	ds_read_b128 v[136:139], v98 offset:36960
	ds_read_b128 v[144:147], v98 offset:41568
	ds_read_b128 v[152:155], v98 offset:46176
	ds_read_b128 v[190:193], v101 offset:96
	ds_read_b128 v[198:201], v101 offset:4704
	s_setprio 1
	s_waitcnt lgkmcnt(6)
	v_mfma_f32_32x32x16_bf16 v[82:97], v[156:159], v[120:123], v[82:97]
	v_mfma_f32_32x32x16_bf16 v[50:65], v[156:159], v[140:143], v[50:65]
	v_mfma_f32_32x32x16_bf16 v[2:17], v[156:159], v[148:151], v[2:17]
	s_waitcnt lgkmcnt(5)
	v_mfma_f32_32x32x16_bf16 v[66:81], v[194:197], v[120:123], v[66:81]
	v_mfma_f32_32x32x16_bf16 v[34:49], v[194:197], v[140:143], v[34:49]
	v_mfma_f32_32x32x16_bf16 v[18:33], v[194:197], v[148:151], v[18:33]
	s_setprio 0
	s_setprio 1
	s_waitcnt lgkmcnt(1)
	v_mfma_f32_32x32x16_bf16 v[82:97], v[190:193], v[136:139], v[82:97]
	v_mfma_f32_32x32x16_bf16 v[50:65], v[190:193], v[144:147], v[50:65]
	v_mfma_f32_32x32x16_bf16 v[2:17], v[190:193], v[152:155], v[2:17]
	s_waitcnt lgkmcnt(0)
	v_mfma_f32_32x32x16_bf16 v[66:81], v[198:201], v[136:139], v[66:81]
	v_mfma_f32_32x32x16_bf16 v[34:49], v[198:201], v[144:147], v[34:49]
	v_mfma_f32_32x32x16_bf16 v[18:33], v[198:201], v[152:155], v[18:33]
	s_setprio 0
	s_barrier
	global_load_dwordx4 v[120:123], v[106:107], off offset:1536
	global_load_dwordx4 v[136:139], v[108:109], off offset:1536
	global_load_dwordx4 v[140:143], v[102:103], off offset:1536
	global_load_dwordx4 v[144:147], v[104:105], off offset:1536
	global_load_dwordx4 v[148:151], v[110:111], off offset:1536
	global_load_dwordx4 v[152:155], v[112:113], off offset:1536
	global_load_dwordx4 v[156:159], v[116:117], off offset:1536
	s_waitcnt vmcnt(11)
	ds_write_b128 v119, v[170:173]
	ds_write_b128 v119, v[162:165] offset:9216
	ds_write_b128 v119, v[166:169] offset:18432
	s_waitcnt vmcnt(9)
	ds_write_b128 v119, v[178:181] offset:27648
	ds_write_b128 v119, v[174:177] offset:36864
	s_waitcnt vmcnt(8)
	ds_write_b128 v119, v[182:185] offset:46080
	s_waitcnt vmcnt(7)
	ds_write_b128 v119, v[186:189] offset:55296
	ds_read_b128 v[162:165], v115 offset:36864
	ds_read_b128 v[166:169], v115 offset:36896
	ds_read_b128 v[170:173], v115 offset:41472
	ds_read_b128 v[174:177], v115 offset:41504
	ds_read_b128 v[178:181], v115 offset:46080
	ds_read_b128 v[182:185], v115 offset:46112
	ds_read_b128 v[186:189], v100
	ds_read_b128 v[190:193], v100 offset:32
	ds_read_b128 v[194:197], v100 offset:4608
	ds_read_b128 v[198:201], v100 offset:4640
	s_setprio 1
	s_waitcnt lgkmcnt(3)
	v_mfma_f32_32x32x16_bf16 v[82:97], v[186:189], v[162:165], v[82:97]
	v_mfma_f32_32x32x16_bf16 v[50:65], v[186:189], v[170:173], v[50:65]
	v_mfma_f32_32x32x16_bf16 v[2:17], v[186:189], v[178:181], v[2:17]
	s_waitcnt lgkmcnt(1)
	v_mfma_f32_32x32x16_bf16 v[66:81], v[194:197], v[162:165], v[66:81]
	v_mfma_f32_32x32x16_bf16 v[34:49], v[194:197], v[170:173], v[34:49]
	v_mfma_f32_32x32x16_bf16 v[18:33], v[194:197], v[178:181], v[18:33]
	s_setprio 0
	ds_read_b128 v[162:165], v115 offset:36928
	ds_read_b128 v[170:173], v115 offset:41536
	ds_read_b128 v[178:181], v115 offset:46144
	ds_read_b128 v[186:189], v100 offset:64
	ds_read_b128 v[194:197], v100 offset:4672
	s_setprio 1
	v_mfma_f32_32x32x16_bf16 v[82:97], v[190:193], v[166:169], v[82:97]
	v_mfma_f32_32x32x16_bf16 v[50:65], v[190:193], v[174:177], v[50:65]
	v_mfma_f32_32x32x16_bf16 v[2:17], v[190:193], v[182:185], v[2:17]
	s_waitcnt lgkmcnt(5)
	v_mfma_f32_32x32x16_bf16 v[66:81], v[198:201], v[166:169], v[66:81]
	v_mfma_f32_32x32x16_bf16 v[34:49], v[198:201], v[174:177], v[34:49]
	v_mfma_f32_32x32x16_bf16 v[18:33], v[198:201], v[182:185], v[18:33]
	s_setprio 0
	ds_read_b128 v[166:169], v115 offset:36960
	ds_read_b128 v[174:177], v115 offset:41568
	ds_read_b128 v[182:185], v115 offset:46176
	ds_read_b128 v[190:193], v100 offset:96
	ds_read_b128 v[198:201], v100 offset:4704
	s_setprio 1
	s_waitcnt lgkmcnt(6)
	v_mfma_f32_32x32x16_bf16 v[82:97], v[186:189], v[162:165], v[82:97]
	v_mfma_f32_32x32x16_bf16 v[50:65], v[186:189], v[170:173], v[50:65]
	v_mfma_f32_32x32x16_bf16 v[2:17], v[186:189], v[178:181], v[2:17]
	s_waitcnt lgkmcnt(5)
	v_mfma_f32_32x32x16_bf16 v[66:81], v[194:197], v[162:165], v[66:81]
	v_mfma_f32_32x32x16_bf16 v[34:49], v[194:197], v[170:173], v[34:49]
	v_mfma_f32_32x32x16_bf16 v[18:33], v[194:197], v[178:181], v[18:33]
	s_setprio 0
	s_setprio 1
	s_waitcnt lgkmcnt(1)
	v_mfma_f32_32x32x16_bf16 v[82:97], v[190:193], v[166:169], v[82:97]
	v_mfma_f32_32x32x16_bf16 v[50:65], v[190:193], v[174:177], v[50:65]
	v_mfma_f32_32x32x16_bf16 v[2:17], v[190:193], v[182:185], v[2:17]
	s_waitcnt lgkmcnt(0)
	v_mfma_f32_32x32x16_bf16 v[66:81], v[198:201], v[166:169], v[66:81]
	v_mfma_f32_32x32x16_bf16 v[34:49], v[198:201], v[174:177], v[34:49]
	v_mfma_f32_32x32x16_bf16 v[18:33], v[198:201], v[182:185], v[18:33]
	s_setprio 0
	s_barrier
	global_load_dwordx4 v[162:165], v[106:107], off offset:1664
	global_load_dwordx4 v[166:169], v[108:109], off offset:1664
	global_load_dwordx4 v[170:173], v[102:103], off offset:1664
	global_load_dwordx4 v[174:177], v[104:105], off offset:1664
	global_load_dwordx4 v[178:181], v[110:111], off offset:1664
	global_load_dwordx4 v[182:185], v[112:113], off offset:1664
	global_load_dwordx4 v[186:189], v[116:117], off offset:1664
	s_waitcnt vmcnt(11)
	ds_write_b128 v114, v[140:143]
	ds_write_b128 v114, v[120:123] offset:9216
	ds_write_b128 v114, v[136:139] offset:18432
	s_waitcnt vmcnt(9)
	ds_write_b128 v114, v[148:151] offset:27648
	ds_write_b128 v114, v[144:147] offset:36864
	s_waitcnt vmcnt(8)
	ds_write_b128 v114, v[152:155] offset:46080
	s_waitcnt vmcnt(7)
	ds_write_b128 v114, v[156:159] offset:55296
	ds_read_b128 v[120:123], v98 offset:36864
	ds_read_b128 v[136:139], v98 offset:36896
	ds_read_b128 v[140:143], v98 offset:41472
	ds_read_b128 v[144:147], v98 offset:41504
	ds_read_b128 v[148:151], v98 offset:46080
	ds_read_b128 v[152:155], v98 offset:46112
	ds_read_b128 v[156:159], v101
	ds_read_b128 v[190:193], v101 offset:32
	ds_read_b128 v[194:197], v101 offset:4608
	ds_read_b128 v[198:201], v101 offset:4640
	s_setprio 1
	s_waitcnt lgkmcnt(3)
	v_mfma_f32_32x32x16_bf16 v[82:97], v[156:159], v[120:123], v[82:97]
	v_mfma_f32_32x32x16_bf16 v[50:65], v[156:159], v[140:143], v[50:65]
	v_mfma_f32_32x32x16_bf16 v[2:17], v[156:159], v[148:151], v[2:17]
	s_waitcnt lgkmcnt(1)
	v_mfma_f32_32x32x16_bf16 v[66:81], v[194:197], v[120:123], v[66:81]
	v_mfma_f32_32x32x16_bf16 v[34:49], v[194:197], v[140:143], v[34:49]
	v_mfma_f32_32x32x16_bf16 v[18:33], v[194:197], v[148:151], v[18:33]
	s_setprio 0
	ds_read_b128 v[120:123], v98 offset:36928
	ds_read_b128 v[140:143], v98 offset:41536
	ds_read_b128 v[148:151], v98 offset:46144
	ds_read_b128 v[156:159], v101 offset:64
	ds_read_b128 v[194:197], v101 offset:4672
	s_setprio 1
	v_mfma_f32_32x32x16_bf16 v[82:97], v[190:193], v[136:139], v[82:97]
	v_mfma_f32_32x32x16_bf16 v[50:65], v[190:193], v[144:147], v[50:65]
	v_mfma_f32_32x32x16_bf16 v[2:17], v[190:193], v[152:155], v[2:17]
	s_waitcnt lgkmcnt(5)
	v_mfma_f32_32x32x16_bf16 v[66:81], v[198:201], v[136:139], v[66:81]
	v_mfma_f32_32x32x16_bf16 v[34:49], v[198:201], v[144:147], v[34:49]
	v_mfma_f32_32x32x16_bf16 v[18:33], v[198:201], v[152:155], v[18:33]
	s_setprio 0
	ds_read_b128 v[136:139], v98 offset:36960
	ds_read_b128 v[144:147], v98 offset:41568
	ds_read_b128 v[152:155], v98 offset:46176
	ds_read_b128 v[190:193], v101 offset:96
	ds_read_b128 v[198:201], v101 offset:4704
	s_setprio 1
	s_waitcnt lgkmcnt(6)
	v_mfma_f32_32x32x16_bf16 v[82:97], v[156:159], v[120:123], v[82:97]
	v_mfma_f32_32x32x16_bf16 v[50:65], v[156:159], v[140:143], v[50:65]
	v_mfma_f32_32x32x16_bf16 v[2:17], v[156:159], v[148:151], v[2:17]
	s_waitcnt lgkmcnt(5)
	v_mfma_f32_32x32x16_bf16 v[66:81], v[194:197], v[120:123], v[66:81]
	v_mfma_f32_32x32x16_bf16 v[34:49], v[194:197], v[140:143], v[34:49]
	v_mfma_f32_32x32x16_bf16 v[18:33], v[194:197], v[148:151], v[18:33]
	s_setprio 0
	s_setprio 1
	s_waitcnt lgkmcnt(1)
	v_mfma_f32_32x32x16_bf16 v[82:97], v[190:193], v[136:139], v[82:97]
	v_mfma_f32_32x32x16_bf16 v[50:65], v[190:193], v[144:147], v[50:65]
	v_mfma_f32_32x32x16_bf16 v[2:17], v[190:193], v[152:155], v[2:17]
	s_waitcnt lgkmcnt(0)
	v_mfma_f32_32x32x16_bf16 v[66:81], v[198:201], v[136:139], v[66:81]
	v_mfma_f32_32x32x16_bf16 v[34:49], v[198:201], v[144:147], v[34:49]
	v_mfma_f32_32x32x16_bf16 v[18:33], v[198:201], v[152:155], v[18:33]
	s_setprio 0
	s_barrier
	global_load_dwordx4 v[120:123], v[106:107], off offset:1792
	global_load_dwordx4 v[136:139], v[108:109], off offset:1792
	global_load_dwordx4 v[140:143], v[102:103], off offset:1792
	global_load_dwordx4 v[144:147], v[104:105], off offset:1792
	global_load_dwordx4 v[148:151], v[110:111], off offset:1792
	global_load_dwordx4 v[152:155], v[112:113], off offset:1792
	global_load_dwordx4 v[156:159], v[116:117], off offset:1792
	s_waitcnt vmcnt(11)
	ds_write_b128 v119, v[170:173]
	ds_write_b128 v119, v[162:165] offset:9216
	ds_write_b128 v119, v[166:169] offset:18432
	s_waitcnt vmcnt(9)
	ds_write_b128 v119, v[178:181] offset:27648
	ds_write_b128 v119, v[174:177] offset:36864
	s_waitcnt vmcnt(8)
	ds_write_b128 v119, v[182:185] offset:46080
	s_waitcnt vmcnt(7)
	ds_write_b128 v119, v[186:189] offset:55296
	ds_read_b128 v[162:165], v115 offset:36864
	ds_read_b128 v[166:169], v115 offset:36896
	ds_read_b128 v[170:173], v115 offset:41472
	ds_read_b128 v[174:177], v115 offset:41504
	ds_read_b128 v[178:181], v115 offset:46080
	ds_read_b128 v[182:185], v115 offset:46112
	ds_read_b128 v[186:189], v100
	ds_read_b128 v[190:193], v100 offset:32
	ds_read_b128 v[194:197], v100 offset:4608
	ds_read_b128 v[198:201], v100 offset:4640
	s_setprio 1
	s_waitcnt lgkmcnt(3)
	v_mfma_f32_32x32x16_bf16 v[82:97], v[186:189], v[162:165], v[82:97]
	v_mfma_f32_32x32x16_bf16 v[50:65], v[186:189], v[170:173], v[50:65]
	v_mfma_f32_32x32x16_bf16 v[2:17], v[186:189], v[178:181], v[2:17]
	s_waitcnt lgkmcnt(1)
	v_mfma_f32_32x32x16_bf16 v[66:81], v[194:197], v[162:165], v[66:81]
	v_mfma_f32_32x32x16_bf16 v[34:49], v[194:197], v[170:173], v[34:49]
	v_mfma_f32_32x32x16_bf16 v[18:33], v[194:197], v[178:181], v[18:33]
	s_setprio 0
	ds_read_b128 v[162:165], v115 offset:36928
	ds_read_b128 v[170:173], v115 offset:41536
	ds_read_b128 v[178:181], v115 offset:46144
	ds_read_b128 v[186:189], v100 offset:64
	ds_read_b128 v[194:197], v100 offset:4672
	s_setprio 1
	v_mfma_f32_32x32x16_bf16 v[82:97], v[190:193], v[166:169], v[82:97]
	v_mfma_f32_32x32x16_bf16 v[50:65], v[190:193], v[174:177], v[50:65]
	v_mfma_f32_32x32x16_bf16 v[2:17], v[190:193], v[182:185], v[2:17]
	s_waitcnt lgkmcnt(5)
	v_mfma_f32_32x32x16_bf16 v[66:81], v[198:201], v[166:169], v[66:81]
	v_mfma_f32_32x32x16_bf16 v[34:49], v[198:201], v[174:177], v[34:49]
	v_mfma_f32_32x32x16_bf16 v[18:33], v[198:201], v[182:185], v[18:33]
	s_setprio 0
	ds_read_b128 v[166:169], v115 offset:36960
	ds_read_b128 v[174:177], v115 offset:41568
	ds_read_b128 v[182:185], v115 offset:46176
	ds_read_b128 v[190:193], v100 offset:96
	ds_read_b128 v[198:201], v100 offset:4704
	s_setprio 1
	s_waitcnt lgkmcnt(6)
	v_mfma_f32_32x32x16_bf16 v[82:97], v[186:189], v[162:165], v[82:97]
	v_mfma_f32_32x32x16_bf16 v[50:65], v[186:189], v[170:173], v[50:65]
	v_mfma_f32_32x32x16_bf16 v[2:17], v[186:189], v[178:181], v[2:17]
	s_waitcnt lgkmcnt(5)
	v_mfma_f32_32x32x16_bf16 v[66:81], v[194:197], v[162:165], v[66:81]
	v_mfma_f32_32x32x16_bf16 v[34:49], v[194:197], v[170:173], v[34:49]
	v_mfma_f32_32x32x16_bf16 v[18:33], v[194:197], v[178:181], v[18:33]
	s_setprio 0
	s_setprio 1
	s_waitcnt lgkmcnt(1)
	v_mfma_f32_32x32x16_bf16 v[82:97], v[190:193], v[166:169], v[82:97]
	v_mfma_f32_32x32x16_bf16 v[50:65], v[190:193], v[174:177], v[50:65]
	v_mfma_f32_32x32x16_bf16 v[2:17], v[190:193], v[182:185], v[2:17]
	s_waitcnt lgkmcnt(0)
	v_mfma_f32_32x32x16_bf16 v[66:81], v[198:201], v[166:169], v[66:81]
	v_mfma_f32_32x32x16_bf16 v[34:49], v[198:201], v[174:177], v[34:49]
	v_mfma_f32_32x32x16_bf16 v[18:33], v[198:201], v[182:185], v[18:33]
	s_setprio 0
	s_barrier
	global_load_dwordx4 v[162:165], v[106:107], off offset:1920
	s_nop 0
	global_load_dwordx4 v[106:109], v[108:109], off offset:1920
	s_nop 0
	global_load_dwordx4 v[166:169], v[102:103], off offset:1920
	s_nop 0
	global_load_dwordx4 v[102:105], v[104:105], off offset:1920
	s_nop 0
	global_load_dwordx4 v[170:173], v[110:111], off offset:1920
	s_nop 0
	global_load_dwordx4 v[110:113], v[112:113], off offset:1920
	s_nop 0
	global_load_dwordx4 v[174:177], v[116:117], off offset:1920
	s_waitcnt vmcnt(11)
	ds_write_b128 v114, v[140:143]
	ds_write_b128 v114, v[120:123] offset:9216
	ds_write_b128 v114, v[136:139] offset:18432
	s_waitcnt vmcnt(9)
	ds_write_b128 v114, v[148:151] offset:27648
	ds_write_b128 v114, v[144:147] offset:36864
	s_waitcnt vmcnt(8)
	ds_write_b128 v114, v[152:155] offset:46080
	s_waitcnt vmcnt(7)
	ds_write_b128 v114, v[156:159] offset:55296
	ds_read_b128 v[120:123], v98 offset:36864
	ds_read_b128 v[136:139], v98 offset:36896
	ds_read_b128 v[140:143], v98 offset:41472
	ds_read_b128 v[144:147], v98 offset:41504
	ds_read_b128 v[148:151], v98 offset:46080
	ds_read_b128 v[152:155], v98 offset:46112
	ds_read_b128 v[156:159], v101
	ds_read_b128 v[178:181], v101 offset:32
	ds_read_b128 v[182:185], v101 offset:4608
	ds_read_b128 v[186:189], v101 offset:4640
	s_setprio 1
	s_waitcnt lgkmcnt(3)
	v_mfma_f32_32x32x16_bf16 v[82:97], v[156:159], v[120:123], v[82:97]
	v_mfma_f32_32x32x16_bf16 v[50:65], v[156:159], v[140:143], v[50:65]
	v_mfma_f32_32x32x16_bf16 v[2:17], v[156:159], v[148:151], v[2:17]
	s_waitcnt lgkmcnt(1)
	v_mfma_f32_32x32x16_bf16 v[66:81], v[182:185], v[120:123], v[66:81]
	v_mfma_f32_32x32x16_bf16 v[34:49], v[182:185], v[140:143], v[34:49]
	v_mfma_f32_32x32x16_bf16 v[18:33], v[182:185], v[148:151], v[18:33]
	s_setprio 0
	ds_read_b128 v[120:123], v98 offset:36928
	ds_read_b128 v[140:143], v98 offset:41536
	ds_read_b128 v[148:151], v98 offset:46144
	ds_read_b128 v[156:159], v101 offset:64
	ds_read_b128 v[182:185], v101 offset:4672
	s_setprio 1
	v_mfma_f32_32x32x16_bf16 v[82:97], v[178:181], v[136:139], v[82:97]
	v_mfma_f32_32x32x16_bf16 v[50:65], v[178:181], v[144:147], v[50:65]
	v_mfma_f32_32x32x16_bf16 v[2:17], v[178:181], v[152:155], v[2:17]
	s_waitcnt lgkmcnt(5)
	v_mfma_f32_32x32x16_bf16 v[66:81], v[186:189], v[136:139], v[66:81]
	v_mfma_f32_32x32x16_bf16 v[34:49], v[186:189], v[144:147], v[34:49]
	v_mfma_f32_32x32x16_bf16 v[18:33], v[186:189], v[152:155], v[18:33]
	s_setprio 0
	ds_read_b128 v[136:139], v98 offset:36960
	ds_read_b128 v[144:147], v98 offset:41568
	ds_read_b128 v[152:155], v98 offset:46176
	ds_read_b128 v[178:181], v101 offset:96
	ds_read_b128 v[186:189], v101 offset:4704
	s_setprio 1
	s_waitcnt lgkmcnt(6)
	v_mfma_f32_32x32x16_bf16 v[82:97], v[156:159], v[120:123], v[82:97]
	v_mfma_f32_32x32x16_bf16 v[50:65], v[156:159], v[140:143], v[50:65]
	v_mfma_f32_32x32x16_bf16 v[2:17], v[156:159], v[148:151], v[2:17]
	s_waitcnt lgkmcnt(5)
	v_mfma_f32_32x32x16_bf16 v[66:81], v[182:185], v[120:123], v[66:81]
	v_mfma_f32_32x32x16_bf16 v[34:49], v[182:185], v[140:143], v[34:49]
	v_mfma_f32_32x32x16_bf16 v[18:33], v[182:185], v[148:151], v[18:33]
	s_setprio 0
	s_setprio 1
	s_waitcnt lgkmcnt(1)
	v_mfma_f32_32x32x16_bf16 v[82:97], v[178:181], v[136:139], v[82:97]
	v_mfma_f32_32x32x16_bf16 v[50:65], v[178:181], v[144:147], v[50:65]
	v_mfma_f32_32x32x16_bf16 v[2:17], v[178:181], v[152:155], v[2:17]
	s_waitcnt lgkmcnt(0)
	v_mfma_f32_32x32x16_bf16 v[66:81], v[186:189], v[136:139], v[66:81]
	v_mfma_f32_32x32x16_bf16 v[34:49], v[186:189], v[144:147], v[34:49]
	v_mfma_f32_32x32x16_bf16 v[18:33], v[186:189], v[152:155], v[18:33]
	s_setprio 0
	s_barrier
	s_waitcnt vmcnt(4)
	ds_write_b128 v119, v[166:169]
	ds_write_b128 v119, v[162:165] offset:9216
	ds_write_b128 v119, v[106:109] offset:18432
	s_waitcnt vmcnt(2)
	ds_write_b128 v119, v[170:173] offset:27648
	ds_write_b128 v119, v[102:105] offset:36864
	s_waitcnt vmcnt(1)
	ds_write_b128 v119, v[110:113] offset:46080
	s_waitcnt vmcnt(0)
	ds_write_b128 v119, v[174:177] offset:55296
	ds_read_b128 v[102:105], v115 offset:36864
	ds_read_b128 v[106:109], v115 offset:36896
	ds_read_b128 v[110:113], v115 offset:41472
	ds_read_b128 v[120:123], v115 offset:41504
	ds_read_b128 v[136:139], v115 offset:46080
	ds_read_b128 v[140:143], v115 offset:46112
	ds_read_b128 v[144:147], v100
	ds_read_b128 v[148:151], v100 offset:32
	ds_read_b128 v[152:155], v100 offset:4608
	ds_read_b128 v[156:159], v100 offset:4640
	s_setprio 1
	s_waitcnt lgkmcnt(3)
	v_mfma_f32_32x32x16_bf16 v[82:97], v[144:147], v[102:105], v[82:97]
	v_mfma_f32_32x32x16_bf16 v[50:65], v[144:147], v[110:113], v[50:65]
	v_mfma_f32_32x32x16_bf16 v[2:17], v[144:147], v[136:139], v[2:17]
	s_waitcnt lgkmcnt(1)
	v_mfma_f32_32x32x16_bf16 v[66:81], v[152:155], v[102:105], v[66:81]
	v_mfma_f32_32x32x16_bf16 v[34:49], v[152:155], v[110:113], v[34:49]
	v_mfma_f32_32x32x16_bf16 v[18:33], v[152:155], v[136:139], v[18:33]
	s_setprio 0
	ds_read_b128 v[102:105], v115 offset:36928
	ds_read_b128 v[110:113], v115 offset:41536
	ds_read_b128 v[136:139], v115 offset:46144
	ds_read_b128 v[144:147], v100 offset:64
	ds_read_b128 v[152:155], v100 offset:4672
	s_setprio 1
	v_mfma_f32_32x32x16_bf16 v[82:97], v[148:151], v[106:109], v[82:97]
	v_mfma_f32_32x32x16_bf16 v[50:65], v[148:151], v[120:123], v[50:65]
	v_mfma_f32_32x32x16_bf16 v[2:17], v[148:151], v[140:143], v[2:17]
	s_waitcnt lgkmcnt(5)
	v_mfma_f32_32x32x16_bf16 v[66:81], v[156:159], v[106:109], v[66:81]
	v_mfma_f32_32x32x16_bf16 v[34:49], v[156:159], v[120:123], v[34:49]
	v_mfma_f32_32x32x16_bf16 v[18:33], v[156:159], v[140:143], v[18:33]
	s_setprio 0
	ds_read_b128 v[106:109], v115 offset:36960
	ds_read_b128 v[120:123], v115 offset:41568
	ds_read_b128 v[114:117], v115 offset:46176
	ds_read_b128 v[140:143], v100 offset:96
	ds_read_b128 v[148:151], v100 offset:4704
	s_setprio 1
	s_waitcnt lgkmcnt(6)
	v_mfma_f32_32x32x16_bf16 v[82:97], v[144:147], v[102:105], v[82:97]
	v_mfma_f32_32x32x16_bf16 v[50:65], v[144:147], v[110:113], v[50:65]
	v_mfma_f32_32x32x16_bf16 v[2:17], v[144:147], v[136:139], v[2:17]
	s_waitcnt lgkmcnt(5)
	v_mfma_f32_32x32x16_bf16 v[66:81], v[152:155], v[102:105], v[66:81]
	v_mfma_f32_32x32x16_bf16 v[34:49], v[152:155], v[110:113], v[34:49]
	v_mfma_f32_32x32x16_bf16 v[18:33], v[152:155], v[136:139], v[18:33]
	s_setprio 0
	s_setprio 1
	s_waitcnt lgkmcnt(1)
	v_mfma_f32_32x32x16_bf16 v[82:97], v[140:143], v[106:109], v[82:97]
	v_mfma_f32_32x32x16_bf16 v[50:65], v[140:143], v[120:123], v[50:65]
	v_mfma_f32_32x32x16_bf16 v[2:17], v[140:143], v[114:117], v[2:17]
	s_waitcnt lgkmcnt(0)
	v_mfma_f32_32x32x16_bf16 v[66:81], v[148:151], v[106:109], v[66:81]
	v_mfma_f32_32x32x16_bf16 v[34:49], v[148:151], v[120:123], v[34:49]
	v_mfma_f32_32x32x16_bf16 v[18:33], v[148:151], v[114:117], v[18:33]
	s_setprio 0
	s_barrier
	ds_read_b128 v[102:105], v98 offset:36864
	ds_read_b128 v[106:109], v98 offset:36896
	ds_read_b128 v[110:113], v98 offset:41472
	ds_read_b128 v[114:117], v98 offset:41504
	ds_read_b128 v[120:123], v98 offset:46080
	ds_read_b128 v[136:139], v98 offset:46112
	ds_read_b128 v[140:143], v101
	ds_read_b128 v[144:147], v101 offset:32
	ds_read_b128 v[148:151], v101 offset:4608
	ds_read_b128 v[152:155], v101 offset:4640
	s_setprio 1
	s_waitcnt lgkmcnt(3)
	v_mfma_f32_32x32x16_bf16 v[82:97], v[140:143], v[102:105], v[82:97]
	v_mfma_f32_32x32x16_bf16 v[50:65], v[140:143], v[110:113], v[50:65]
	v_mfma_f32_32x32x16_bf16 v[2:17], v[140:143], v[120:123], v[2:17]
	s_waitcnt lgkmcnt(1)
	v_mfma_f32_32x32x16_bf16 v[66:81], v[148:151], v[102:105], v[66:81]
	v_mfma_f32_32x32x16_bf16 v[34:49], v[148:151], v[110:113], v[34:49]
	v_mfma_f32_32x32x16_bf16 v[18:33], v[148:151], v[120:123], v[18:33]
	s_setprio 0
	ds_read_b128 v[102:105], v98 offset:36928
	ds_read_b128 v[110:113], v98 offset:41536
	ds_read_b128 v[120:123], v98 offset:46144
	ds_read_b128 v[140:143], v101 offset:64
	ds_read_b128 v[148:151], v101 offset:4672
	s_setprio 1
	v_mfma_f32_32x32x16_bf16 v[82:97], v[144:147], v[106:109], v[82:97]
	v_mfma_f32_32x32x16_bf16 v[50:65], v[144:147], v[114:117], v[50:65]
	v_mfma_f32_32x32x16_bf16 v[2:17], v[144:147], v[136:139], v[2:17]
	s_waitcnt lgkmcnt(5)
	v_mfma_f32_32x32x16_bf16 v[66:81], v[152:155], v[106:109], v[66:81]
	v_mfma_f32_32x32x16_bf16 v[34:49], v[152:155], v[114:117], v[34:49]
	v_mfma_f32_32x32x16_bf16 v[18:33], v[152:155], v[136:139], v[18:33]
	s_setprio 0
	ds_read_b128 v[106:109], v98 offset:36960
	ds_read_b128 v[114:117], v98 offset:41568
	ds_read_b128 v[136:139], v98 offset:46176
	ds_read_b128 v[144:147], v101 offset:96
	ds_read_b128 v[152:155], v101 offset:4704
	s_setprio 1
	s_waitcnt lgkmcnt(6)
	v_mfma_f32_32x32x16_bf16 v[82:97], v[140:143], v[102:105], v[82:97]
	v_mfma_f32_32x32x16_bf16 v[50:65], v[140:143], v[110:113], v[50:65]
	v_mfma_f32_32x32x16_bf16 v[2:17], v[140:143], v[120:123], v[2:17]
	s_waitcnt lgkmcnt(5)
	v_mfma_f32_32x32x16_bf16 v[66:81], v[148:151], v[102:105], v[66:81]
	v_mfma_f32_32x32x16_bf16 v[34:49], v[148:151], v[110:113], v[34:49]
	v_mfma_f32_32x32x16_bf16 v[18:33], v[148:151], v[120:123], v[18:33]
	s_setprio 0
	s_setprio 1
	s_waitcnt lgkmcnt(1)
	v_mfma_f32_32x32x16_bf16 v[82:97], v[144:147], v[106:109], v[82:97]
	v_mfma_f32_32x32x16_bf16 v[50:65], v[144:147], v[114:117], v[50:65]
	v_mfma_f32_32x32x16_bf16 v[2:17], v[144:147], v[136:139], v[2:17]
	s_waitcnt lgkmcnt(0)
	v_mfma_f32_32x32x16_bf16 v[66:81], v[152:155], v[106:109], v[66:81]
	v_mfma_f32_32x32x16_bf16 v[34:49], v[152:155], v[114:117], v[34:49]
	v_mfma_f32_32x32x16_bf16 v[18:33], v[152:155], v[136:139], v[18:33]
	s_setprio 0
	s_add_i32 s98, s61, s62
	s_cmpk_lt_i32 s98, 0x700
	s_cbranch_scc0 .Lg1x_nopf
	s_abs_i32 s33, s98
	s_mul_hi_u32 s94, s33, s53
	s_mul_i32 s95, s94, s49
	s_ashr_i32 s32, s98, 31
	s_sub_i32 s33, s33, s95
	s_xor_b32 s32, s32, s51
	s_add_i32 s95, s94, 1
	s_sub_i32 s100, s33, s49
	s_cmp_ge_u32 s33, s49
	s_cselect_b32 s94, s95, s94
	s_cselect_b32 s33, s100, s33
	s_add_i32 s95, s94, 1
	s_cmp_ge_u32 s33, s49
	s_cselect_b32 s33, s95, s94
	s_xor_b32 s33, s33, s32
	s_sub_i32 s32, s33, s32
	s_mul_i32 s33, s52, s32
	s_add_i32 s33, s98, s33
	s_and_b32 s94, s33, 7
	s_ashr_i32 s33, s33, 3
	s_mul_i32 s32, s32, s44
	s_add_i32 s32, s32, s33
	s_mul_hi_i32 s33, s32, 0x92492493
	s_add_i32 s33, s33, s32
	s_lshr_b32 s95, s33, 31
	s_ashr_i32 s33, s33, 5
	s_add_i32 s33, s33, s95
	s_mul_i32 s95, s33, 0xffffffc8
	s_add_i32 s95, s95, s32
	s_lshl_b32 s32, s33, 3
	s_or_b32 s32, s32, s94
	s_lshr_b32 s33, s32, 31
	s_add_i32 s33, s32, s33
	s_and_b32 s94, s33, -2
	s_sub_i32 s32, s32, s94
	s_mul_hi_i32 s94, s95, 0x92492493
	s_add_i32 s94, s94, s95
	s_lshr_b32 s100, s94, 31
	s_ashr_i32 s94, s94, 2
	s_add_i32 s94, s94, s100
	s_mul_i32 s100, s94, 7
	s_mul_i32 s32, s32, 7
	s_sub_i32 s95, s95, s100
	s_add_i32 s101, s32, s95
	s_lshl_b32 s32, s33, 2
	s_and_b32 s32, s32, -8
	s_add_i32 s99, s32, s94
	s_lshl_b32 s32, s101, 19
	s_add_u32 s32, s45, s32
	s_addc_u32 s33, s46, 0
	s_mul_i32 s94, s99, 0x60000
	s_add_u32 s94, s47, s94
	s_addc_u32 s95, s48, 0
	v_lshrrev_b32_e32 v162, 3, v212
	v_and_b32_e32 v163, 7, v212
	v_lshlrev_b32_e32 v162, 11, v162
	v_lshl_or_b32 v162, v163, 4, v162
	v_add_u32_e32 v163, 0x20000, v162
	v_add_u32_e32 v164, 0x40000, v162
	v_add_u32_e32 v165, 0x60000, v162
	global_load_dwordx4 v[214:217], v162, s[32:33]
	global_load_dwordx4 v[218:221], v163, s[32:33]
	global_load_dwordx4 v[222:225], v164, s[32:33]
	global_load_dwordx4 v[226:229], v165, s[32:33]
	global_load_dwordx4 v[230:233], v162, s[94:95]
	global_load_dwordx4 v[234:237], v163, s[94:95]
	global_load_dwordx4 v[238:241], v164, s[94:95]
	global_load_dwordx4 v[194:197], v162, s[32:33] offset:128
	global_load_dwordx4 v[198:201], v163, s[32:33] offset:128
	global_load_dwordx4 v[246:249], v164, s[32:33] offset:128
	global_load_dwordx4 v[250:253], v165, s[32:33] offset:128
	global_load_dwordx4 v[186:189], v162, s[94:95] offset:128
	global_load_dwordx4 v[190:193], v163, s[94:95] offset:128
	global_load_dwordx2 v[242:243], v164, s[94:95] offset:128
	global_load_dwordx2 v[254:255], v164, s[94:95] offset:136
	s_mov_b32 s101, 1
	s_branch .Lg1x_pfd
.Lg1x_nopf:
	s_mov_b32 s101, 0
.Lg1x_pfd:
	s_cmp_lt_i32 s9, 43
	s_cselect_b64 s[10:11], -1, 0
	s_and_b32 s3, s8, -4
	s_cmp_eq_u32 s3, 8
	s_cselect_b64 s[8:9], -1, 0
	s_and_b64 s[8:9], s[10:11], s[8:9]
	s_andn2_b64 vcc, exec, s[8:9]
	s_barrier

.LBB0_244:
	s_or_b64 exec, exec, s[14:15]
	v_pk_mul_f32 v[70:71], v[104:105], v[70:71]
	v_pk_mul_f32 v[72:73], v[104:105], v[72:73]
	v_pk_mul_f32 v[66:67], v[104:105], v[66:67]
	v_cvt_pk_bf16_f32 v70, v70, v71
	v_cvt_pk_bf16_f32 v71, v72, v73
	v_cvt_pk_bf16_f32 v72, v66, v67
	v_pk_mul_f32 v[66:67], v[104:105], v[68:69]
	s_and_b64 s[12:13], s[4:5], s[12:13]
	v_cvt_pk_bf16_f32 v73, v66, v67
	ds_write_b128 v202, v[70:73] offset:48
	ds_read_b128 v[176:179], v204
	ds_read_b128 v[180:183], v204 offset:144
	s_cmp_lg_u64 s[98:99], 0
	s_cbranch_scc0 .Lg1co_k0
	v_lshl_add_u64 v[184:185], v[122:123], 0, v[206:207]
	s_waitcnt lgkmcnt(1)
	global_store_dwordx4 v[184:185], v[176:179], off
	ds_read_b128 v[176:179], v204 offset:288
	s_waitcnt lgkmcnt(1)
	global_store_dwordx4 v[184:185], v[180:183], off offset:1024
	ds_read_b128 v[180:183], v204 offset:432
	s_waitcnt lgkmcnt(1)
	global_store_dwordx4 v[184:185], v[176:179], off offset:2048
	s_waitcnt lgkmcnt(0)
	global_store_dwordx4 v[184:185], v[180:183], off offset:3072
	s_branch .Lg1co_e0
.Lg1co_k0:
	v_lshl_add_u64 v[184:185], v[122:123], 0, v[208:209]
	s_waitcnt lgkmcnt(1)
	global_store_dwordx4 v[184:185], v[176:179], off
	ds_read_b128 v[176:179], v204 offset:288
	s_waitcnt lgkmcnt(1)
	global_store_dwordx4 v[184:185], v[180:183], off offset:128
	ds_read_b128 v[180:183], v204 offset:432
	s_waitcnt lgkmcnt(1)
	global_store_dwordx4 v[184:185], v[176:179], off offset:256
	s_waitcnt lgkmcnt(0)
	global_store_dwordx4 v[184:185], v[180:183], off offset:384

.LBB0_263:
	s_andn2_saveexec_b64 s[12:13], s[36:37]
	s_cbranch_execz .LBB0_265
	v_mul_f32_e32 v105, 0xbfb8aa3b, v82
	v_mul_f32_e32 v109, 0xbfb8aa3b, v66
	v_mul_f32_e32 v117, 0xbfb8aa3b, v83
	v_exp_f32_e32 v105, v105
	v_exp_f32_e32 v109, v109
	v_exp_f32_e32 v117, v117
	v_ashrrev_i32_e32 v119, 31, v118
	v_add_f32_e32 v105, 1.0, v105
	v_add_f32_e32 v109, 1.0, v109
	v_add_f32_e32 v117, 1.0, v117
	v_rcp_f32_e32 v105, v105
	v_rcp_f32_e32 v109, v109
	v_rcp_f32_e32 v117, v117
	v_lshlrev_b64 v[118:119], 10, v[118:119]
	v_lshl_add_u64 v[118:119], v[114:115], 0, v[118:119]
	v_cndmask_b32_e32 v120, v133, v134, vcc
	v_mov_b32_e32 v121, v99
	v_lshl_add_u64 v[118:119], v[118:119], 0, v[120:121]
	v_mul_f32_e32 v120, 0xbfb8aa3b, v67
	v_mul_f32_e32 v82, v82, v105
	v_mul_f32_e32 v105, v66, v109
	v_mul_f32_e32 v83, v83, v117
	v_mul_f32_e32 v109, 0xbfb8aa3b, v84
	v_mul_f32_e32 v117, 0xbfb8aa3b, v68
	v_exp_f32_e32 v120, v120
	v_exp_f32_e32 v109, v109
	v_exp_f32_e32 v117, v117
	v_permlane32_swap_b32_e32 v82, v105
	v_add_f32_e32 v66, 1.0, v120
	v_add_f32_e32 v109, 1.0, v109
	v_add_f32_e32 v117, 1.0, v117
	v_rcp_f32_e32 v66, v66
	v_rcp_f32_e32 v109, v109
	v_rcp_f32_e32 v117, v117
	v_mul_f32_e32 v120, 0xbfb8aa3b, v85
	v_mul_f32_e32 v121, v67, v66
	v_mul_f32_e32 v84, v84, v109
	v_mul_f32_e32 v109, v68, v117
	v_mul_f32_e32 v67, 0xbfb8aa3b, v69
	v_mul_f32_e32 v68, 0xbfb8aa3b, v86
	v_exp_f32_e32 v67, v67
	v_exp_f32_e32 v68, v68
	v_exp_f32_e32 v120, v120
	v_mul_f32_e32 v117, 0xbfb8aa3b, v70
	v_add_f32_e32 v67, 1.0, v67
	v_add_f32_e32 v68, 1.0, v68
	v_rcp_f32_e32 v67, v67
	v_rcp_f32_e32 v68, v68
	v_add_f32_e32 v66, 1.0, v120
	v_rcp_f32_e32 v66, v66
	v_mul_f32_e32 v69, v69, v67
	v_mul_f32_e32 v86, v86, v68
	v_mul_f32_e32 v67, 0xbfb8aa3b, v87
	v_mul_f32_e32 v68, 0xbfb8aa3b, v71
	v_exp_f32_e32 v67, v67
	v_exp_f32_e32 v68, v68
	v_exp_f32_e32 v117, v117
	v_mul_f32_e32 v85, v85, v66
	v_add_f32_e32 v67, 1.0, v67
	v_add_f32_e32 v68, 1.0, v68
	v_rcp_f32_e32 v67, v67
	v_rcp_f32_e32 v68, v68
	v_add_f32_e32 v66, 1.0, v117
	v_mul_f32_e32 v117, 0xbfb8aa3b, v88
	v_mul_f32_e32 v87, v87, v67
	v_mul_f32_e32 v122, v71, v68
	v_mul_f32_e32 v67, 0xbfb8aa3b, v72
	v_mul_f32_e32 v68, 0xbfb8aa3b, v89
	v_exp_f32_e32 v67, v67
	v_exp_f32_e32 v68, v68
	v_rcp_f32_e32 v66, v66
	v_exp_f32_e32 v117, v117
	v_add_f32_e32 v67, 1.0, v67
	v_add_f32_e32 v68, 1.0, v68
	v_rcp_f32_e32 v67, v67
	v_rcp_f32_e32 v68, v68
	v_mul_f32_e32 v120, v70, v66
	v_add_f32_e32 v66, 1.0, v117
	v_mul_f32_e32 v72, v72, v67
	v_mul_f32_e32 v89, v89, v68
	v_mul_f32_e32 v67, 0xbfb8aa3b, v90
	v_mul_f32_e32 v68, 0xbfb8aa3b, v74
	v_exp_f32_e32 v67, v67
	v_exp_f32_e32 v68, v68
	v_mul_f32_e32 v70, 0xbfb8aa3b, v73
	v_rcp_f32_e32 v66, v66
	v_add_f32_e32 v67, 1.0, v67
	v_add_f32_e32 v68, 1.0, v68
	v_rcp_f32_e32 v67, v67
	v_rcp_f32_e32 v68, v68
	v_exp_f32_e32 v70, v70
	v_mul_f32_e32 v88, v88, v66
	v_mul_f32_e32 v90, v90, v67
	v_mul_f32_e32 v74, v74, v68
	v_mul_f32_e32 v67, 0xbfb8aa3b, v75
	v_mul_f32_e32 v68, 0xbfb8aa3b, v92
	v_exp_f32_e32 v67, v67
	v_exp_f32_e32 v68, v68
	v_add_f32_e32 v66, 1.0, v70
	v_mul_f32_e32 v70, 0xbfb8aa3b, v91
	v_add_f32_e32 v67, 1.0, v67
	v_add_f32_e32 v68, 1.0, v68
	v_rcp_f32_e32 v67, v67
	v_rcp_f32_e32 v68, v68
	v_rcp_f32_e32 v66, v66
	v_exp_f32_e32 v70, v70
	v_mul_f32_e32 v75, v75, v67
	v_mul_f32_e32 v92, v92, v68
	v_mul_f32_e32 v67, 0xbfb8aa3b, v93
	v_mul_f32_e32 v68, 0xbfb8aa3b, v77
	v_exp_f32_e32 v67, v67
	v_exp_f32_e32 v68, v68
	v_mul_f32_e32 v73, v73, v66
	v_add_f32_e32 v66, 1.0, v70
	v_mul_f32_e32 v70, 0xbfb8aa3b, v76
	v_add_f32_e32 v67, 1.0, v67
	v_add_f32_e32 v68, 1.0, v68
	v_rcp_f32_e32 v66, v66
	v_exp_f32_e32 v70, v70
	v_rcp_f32_e32 v67, v67
	v_rcp_f32_e32 v68, v68
	v_mul_f32_e32 v91, v91, v66
	v_add_f32_e32 v66, 1.0, v70
	v_mul_f32_e32 v70, 0xbfb8aa3b, v94
	v_mul_f32_e32 v93, v93, v67
	v_mul_f32_e32 v77, v77, v68
	v_mul_f32_e32 v67, 0xbfb8aa3b, v78
	v_mul_f32_e32 v68, 0xbfb8aa3b, v95
	v_rcp_f32_e32 v66, v66
	v_exp_f32_e32 v70, v70
	v_exp_f32_e32 v67, v67
	v_exp_f32_e32 v68, v68
	v_mul_f32_e32 v76, v76, v66
	v_add_f32_e32 v66, 1.0, v70
	v_add_f32_e32 v67, 1.0, v67
	v_add_f32_e32 v68, 1.0, v68
	v_mul_f32_e32 v70, 0xbfb8aa3b, v79
	v_rcp_f32_e32 v66, v66
	v_rcp_f32_e32 v67, v67
	v_rcp_f32_e32 v68, v68
	v_exp_f32_e32 v70, v70
	v_mul_f32_e32 v94, v94, v66
	v_mul_f32_e32 v78, v78, v67
	v_mul_f32_e32 v95, v95, v68
	v_add_f32_e32 v66, 1.0, v70
	v_mul_f32_e32 v67, 0xbfb8aa3b, v96
	v_mul_f32_e32 v68, 0xbfb8aa3b, v80
	v_rcp_f32_e32 v66, v66
	v_exp_f32_e32 v67, v67
	v_exp_f32_e32 v68, v68
	v_mul_f32_e32 v70, 0xbfb8aa3b, v81
	v_mul_f32_e32 v79, v79, v66
	v_add_f32_e32 v66, 1.0, v67
	v_add_f32_e32 v67, 1.0, v68
	v_mul_f32_e32 v68, 0xbfb8aa3b, v97
	v_exp_f32_e32 v68, v68
	v_exp_f32_e32 v70, v70
	v_rcp_f32_e32 v66, v66
	v_rcp_f32_e32 v67, v67
	v_add_f32_e32 v68, 1.0, v68
	v_add_f32_e32 v70, 1.0, v70
	v_rcp_f32_e32 v68, v68
	v_rcp_f32_e32 v70, v70
	v_mul_f32_e32 v96, v96, v66
	v_mul_f32_e32 v80, v80, v67
	v_permlane32_swap_b32_e32 v83, v121
	v_permlane32_swap_b32_e32 v84, v109
	v_permlane32_swap_b32_e32 v85, v69
	v_lshlrev_b32_e32 v66, 1, v100
	v_mov_b32_e32 v67, v99
	v_mul_f32_e32 v97, v97, v68
	v_mul_f32_e32 v81, v81, v70
	v_permlane32_swap_b32_e32 v86, v120
	v_permlane32_swap_b32_e32 v87, v122
	v_permlane32_swap_b32_e32 v88, v72
	v_permlane32_swap_b32_e32 v89, v73
	v_lshl_add_u64 v[70:71], v[118:119], 0, v[66:67]
	v_cvt_pk_bf16_f32 v66, v82, v83
	v_cvt_pk_bf16_f32 v67, v84, v85
	v_cvt_pk_bf16_f32 v68, v105, v121
	v_cvt_pk_bf16_f32 v69, v109, v69
	v_permlane32_swap_b32_e32 v90, v74
	v_permlane32_swap_b32_e32 v91, v75
	v_permlane32_swap_b32_e32 v92, v76
	v_permlane32_swap_b32_e32 v93, v77
	ds_write_b128 v202, v[66:69]
	v_permlane32_swap_b32_e32 v94, v78
	s_nop 0
	v_cvt_pk_bf16_f32 v66, v86, v87
	v_cvt_pk_bf16_f32 v67, v88, v89
	v_cvt_pk_bf16_f32 v68, v120, v122
	v_cvt_pk_bf16_f32 v69, v72, v73
	v_permlane32_swap_b32_e32 v95, v79
	v_permlane32_swap_b32_e32 v96, v80
	v_permlane32_swap_b32_e32 v97, v81
	ds_write_b128 v202, v[66:69] offset:16
	s_nop 1
	v_cvt_pk_bf16_f32 v66, v90, v91
	v_cvt_pk_bf16_f32 v67, v92, v93
	v_cvt_pk_bf16_f32 v68, v74, v75
	v_cvt_pk_bf16_f32 v69, v76, v77
	ds_write_b128 v202, v[66:69] offset:32
	s_nop 1
	v_cvt_pk_bf16_f32 v66, v94, v95
	v_cvt_pk_bf16_f32 v67, v96, v97
	v_cvt_pk_bf16_f32 v68, v78, v79
	v_cvt_pk_bf16_f32 v69, v80, v81
	ds_write_b128 v202, v[66:69] offset:48
	v_lshl_add_u64 v[184:185], v[70:71], 0, v[206:207]
	ds_read_b128 v[176:179], v204
	ds_read_b128 v[180:183], v204 offset:144
	s_waitcnt lgkmcnt(1)
	global_store_dwordx4 v[184:185], v[176:179], off
	ds_read_b128 v[176:179], v204 offset:288
	s_waitcnt lgkmcnt(1)
	global_store_dwordx4 v[184:185], v[180:183], off offset:1024
	ds_read_b128 v[180:183], v204 offset:432
	s_waitcnt lgkmcnt(1)
	global_store_dwordx4 v[184:185], v[176:179], off offset:2048
	s_waitcnt lgkmcnt(0)
	global_store_dwordx4 v[184:185], v[180:183], off offset:3072

.LBB0_266:
	s_or_saveexec_b64 s[14:15], s[34:35]
	v_ashrrev_i32_e32 v116, 1, v116
	v_ashrrev_i32_e32 v117, 31, v116
	v_lshl_add_u64 v[116:117], v[116:117], 1, s[18:19]
	v_lshl_add_u64 v[116:117], v[116:117], 0, v[100:101]
	s_xor_b64 exec, exec, s[14:15]
	s_cbranch_execz .LBB0_268
	v_mul_f32_e32 v66, 0xbfb8aa3b, v66
	v_mul_f32_e32 v67, 0xbfb8aa3b, v67
	v_exp_f32_e32 v66, v66
	v_exp_f32_e32 v67, v67
	v_mul_f32_e32 v68, 0xbfb8aa3b, v68
	v_exp_f32_e32 v68, v68
	v_add_f32_e32 v66, 1.0, v66
	v_add_f32_e32 v67, 1.0, v67
	v_rcp_f32_e32 v66, v66
	v_rcp_f32_e32 v67, v67
	v_cmp_gt_i32_e64 s[12:13], s57, v118
	v_mul_f32_e32 v82, v82, v66
	v_mul_f32_e32 v83, v83, v67
	v_add_f32_e32 v66, 1.0, v68
	v_mul_f32_e32 v67, 0xbfb8aa3b, v69
	v_mul_f32_e32 v68, 0xbfb8aa3b, v70
	v_exp_f32_e32 v67, v67
	v_exp_f32_e32 v68, v68
	v_mul_f32_e32 v69, 0xbfb8aa3b, v71
	v_rcp_f32_e32 v66, v66
	v_add_f32_e32 v67, 1.0, v67
	v_add_f32_e32 v68, 1.0, v68
	v_rcp_f32_e32 v67, v67
	v_rcp_f32_e32 v68, v68
	v_exp_f32_e32 v69, v69
	v_mul_f32_e32 v84, v84, v66
	v_mul_f32_e32 v85, v85, v67
	v_mul_f32_e32 v86, v86, v68
	v_mul_f32_e32 v67, 0xbfb8aa3b, v72
	v_mul_f32_e32 v68, 0xbfb8aa3b, v73
	v_exp_f32_e32 v67, v67
	v_exp_f32_e32 v68, v68
	v_add_f32_e32 v66, 1.0, v69
	v_mul_f32_e32 v69, 0xbfb8aa3b, v74
	v_add_f32_e32 v67, 1.0, v67
	v_add_f32_e32 v68, 1.0, v68
	v_rcp_f32_e32 v67, v67
	v_rcp_f32_e32 v68, v68
	v_rcp_f32_e32 v66, v66
	v_exp_f32_e32 v69, v69
	v_mul_f32_e32 v73, v88, v67
	v_mul_f32_e32 v74, v89, v68
	v_mul_f32_e32 v67, 0xbfb8aa3b, v75
	v_mul_f32_e32 v68, 0xbfb8aa3b, v76
	v_exp_f32_e32 v67, v67
	v_exp_f32_e32 v68, v68
	v_mul_f32_e32 v72, v87, v66
	v_add_f32_e32 v66, 1.0, v69
	v_add_f32_e32 v67, 1.0, v67
	v_add_f32_e32 v68, 1.0, v68
	v_mul_f32_e32 v69, 0xbfb8aa3b, v77
	v_rcp_f32_e32 v66, v66
	v_rcp_f32_e32 v67, v67
	v_rcp_f32_e32 v68, v68
	v_exp_f32_e32 v69, v69
	v_mul_f32_e32 v75, v90, v66
	v_mul_f32_e32 v76, v91, v67
	v_mul_f32_e32 v77, v92, v68
	v_add_f32_e32 v66, 1.0, v69
	v_mul_f32_e32 v67, 0xbfb8aa3b, v78
	v_mul_f32_e32 v68, 0xbfb8aa3b, v79
	v_rcp_f32_e32 v66, v66
	v_exp_f32_e32 v67, v67
	v_exp_f32_e32 v68, v68
	v_mul_f32_e32 v70, 0xbfb8aa3b, v81
	v_mul_f32_e32 v69, v93, v66
	v_add_f32_e32 v66, 1.0, v67
	v_add_f32_e32 v67, 1.0, v68
	v_rcp_f32_e32 v67, v67
	v_mul_f32_e32 v68, 0xbfb8aa3b, v80
	v_rcp_f32_e32 v66, v66
	v_exp_f32_e32 v68, v68
	v_exp_f32_e32 v70, v70
	v_mul_f32_e32 v79, v95, v67
	v_add_u32_e32 v67, 0xffffe000, v108
	v_lshrrev_b32_e32 v67, 12, v67
	v_add_f32_e32 v68, 1.0, v68
	v_add_f32_e32 v70, 1.0, v70
	v_mul_f32_e32 v78, v94, v66
	v_ashrrev_i32_e32 v66, 8, v108
	v_add_u32_e32 v67, 32, v67
	v_rcp_f32_e32 v68, v68
	v_rcp_f32_e32 v70, v70
	v_cndmask_b32_e64 v66, v67, v66, s[12:13]
	v_lshlrev_b32_e32 v66, 5, v66
	v_add3_u32 v66, v118, v66, 16
	v_ashrrev_i32_e32 v67, 31, v66
	v_mul_f32_e32 v80, v96, v68
	v_mul_f32_e32 v81, v97, v70
	v_permlane32_swap_b32_e32 v82, v75
	v_permlane32_swap_b32_e32 v83, v76
	v_permlane32_swap_b32_e32 v84, v77
	v_permlane32_swap_b32_e32 v85, v69
	v_lshlrev_b64 v[66:67], 10, v[66:67]
	v_permlane32_swap_b32_e32 v86, v78
	v_permlane32_swap_b32_e32 v72, v79
	v_permlane32_swap_b32_e32 v73, v80
	v_permlane32_swap_b32_e32 v74, v81
	v_lshl_add_u64 v[70:71], v[116:117], 0, v[66:67]
	v_cvt_pk_bf16_f32 v66, v82, v83
	v_cvt_pk_bf16_f32 v67, v84, v85
	v_cvt_pk_bf16_f32 v68, v75, v76
	v_cvt_pk_bf16_f32 v69, v77, v69
	ds_write_b128 v203, v[66:69]
	s_nop 1
	v_cvt_pk_bf16_f32 v66, v86, v72
	v_cvt_pk_bf16_f32 v67, v73, v74
	v_cvt_pk_bf16_f32 v68, v78, v79
	v_cvt_pk_bf16_f32 v69, v80, v81
	ds_write_b128 v203, v[66:69] offset:16
	v_lshl_add_u64 v[184:185], v[70:71], 0, v[210:211]
	ds_read_b128 v[176:179], v205
	ds_read_b128 v[180:183], v205 offset:144
	s_waitcnt lgkmcnt(1)
	global_store_dwordx4 v[184:185], v[176:179], off
	s_waitcnt lgkmcnt(0)
	global_store_dwordx4 v[184:185], v[180:183], off offset:1024

.LBB0_302:
	s_or_b64 exec, exec, s[14:15]
	v_pk_mul_f32 v[38:39], v[104:105], v[38:39]
	v_pk_mul_f32 v[40:41], v[104:105], v[40:41]
	v_pk_mul_f32 v[34:35], v[104:105], v[34:35]
	v_cvt_pk_bf16_f32 v38, v38, v39
	v_cvt_pk_bf16_f32 v39, v40, v41
	v_cvt_pk_bf16_f32 v40, v34, v35
	v_pk_mul_f32 v[34:35], v[104:105], v[36:37]
	s_and_b64 s[12:13], s[4:5], s[12:13]
	v_cvt_pk_bf16_f32 v41, v34, v35
	ds_write_b128 v202, v[38:41] offset:48
	ds_read_b128 v[176:179], v204
	ds_read_b128 v[180:183], v204 offset:144
	s_cmp_lg_u64 s[98:99], 0
	s_cbranch_scc0 .Lg1co_k3
	v_lshl_add_u64 v[184:185], v[72:73], 0, v[206:207]
	s_waitcnt lgkmcnt(1)
	global_store_dwordx4 v[184:185], v[176:179], off
	ds_read_b128 v[176:179], v204 offset:288
	s_waitcnt lgkmcnt(1)
	global_store_dwordx4 v[184:185], v[180:183], off offset:1024
	ds_read_b128 v[180:183], v204 offset:432
	s_waitcnt lgkmcnt(1)
	global_store_dwordx4 v[184:185], v[176:179], off offset:2048
	s_waitcnt lgkmcnt(0)
	global_store_dwordx4 v[184:185], v[180:183], off offset:3072
	s_branch .Lg1co_e3
.Lg1co_k3:
	v_lshl_add_u64 v[184:185], v[72:73], 0, v[208:209]
	s_waitcnt lgkmcnt(1)
	global_store_dwordx4 v[184:185], v[176:179], off
	ds_read_b128 v[176:179], v204 offset:288
	s_waitcnt lgkmcnt(1)
	global_store_dwordx4 v[184:185], v[180:183], off offset:128
	ds_read_b128 v[180:183], v204 offset:432
	s_waitcnt lgkmcnt(1)
	global_store_dwordx4 v[184:185], v[176:179], off offset:256
	s_waitcnt lgkmcnt(0)
	global_store_dwordx4 v[184:185], v[180:183], off offset:384

.LBB0_321:
	s_andn2_saveexec_b64 s[12:13], s[36:37]
	s_cbranch_execz .LBB0_323
	v_ashrrev_i32_e32 v69, 31, v68
	v_lshlrev_b64 v[66:67], 10, v[68:69]
	v_mul_f32_e32 v68, 0xbfb8aa3b, v50
	v_exp_f32_e32 v70, v68
	v_lshl_add_u64 v[66:67], v[114:115], 0, v[66:67]
	v_cndmask_b32_e32 v68, v133, v134, vcc
	v_mov_b32_e32 v69, v99
	v_lshl_add_u64 v[66:67], v[66:67], 0, v[68:69]
	v_add_f32_e32 v68, 1.0, v70
	v_mul_f32_e32 v69, 0xbfb8aa3b, v34
	v_mul_f32_e32 v70, 0xbfb8aa3b, v51
	v_exp_f32_e32 v69, v69
	v_exp_f32_e32 v70, v70
	v_rcp_f32_e32 v68, v68
	v_mul_f32_e32 v71, 0xbfb8aa3b, v35
	v_add_f32_e32 v69, 1.0, v69
	v_add_f32_e32 v70, 1.0, v70
	v_rcp_f32_e32 v69, v69
	v_rcp_f32_e32 v70, v70
	v_mul_f32_e32 v50, v50, v68
	v_exp_f32_e32 v71, v71
	v_mul_f32_e32 v68, v34, v69
	v_mul_f32_e32 v51, v51, v70
	v_mul_f32_e32 v69, 0xbfb8aa3b, v52
	v_mul_f32_e32 v70, 0xbfb8aa3b, v36
	v_exp_f32_e32 v69, v69
	v_exp_f32_e32 v70, v70
	v_add_f32_e32 v34, 1.0, v71
	v_rcp_f32_e32 v34, v34
	v_add_f32_e32 v69, 1.0, v69
	v_add_f32_e32 v70, 1.0, v70
	v_rcp_f32_e32 v69, v69
	v_rcp_f32_e32 v70, v70
	v_mul_f32_e32 v72, v35, v34
	v_mul_f32_e32 v35, 0xbfb8aa3b, v37
	v_mul_f32_e32 v52, v52, v69
	v_mul_f32_e32 v69, v36, v70
	v_mul_f32_e32 v36, 0xbfb8aa3b, v54
	v_exp_f32_e32 v35, v35
	v_exp_f32_e32 v36, v36
	v_mul_f32_e32 v71, 0xbfb8aa3b, v53
	v_exp_f32_e32 v71, v71
	v_add_f32_e32 v35, 1.0, v35
	v_add_f32_e32 v36, 1.0, v36
	v_rcp_f32_e32 v35, v35
	v_rcp_f32_e32 v36, v36
	v_add_f32_e32 v34, 1.0, v71
	v_mul_f32_e32 v70, 0xbfb8aa3b, v38
	v_mul_f32_e32 v37, v37, v35
	v_mul_f32_e32 v54, v54, v36
	v_mul_f32_e32 v35, 0xbfb8aa3b, v55
	v_mul_f32_e32 v36, 0xbfb8aa3b, v39
	v_exp_f32_e32 v35, v35
	v_exp_f32_e32 v36, v36
	v_rcp_f32_e32 v34, v34
	v_exp_f32_e32 v70, v70
	v_add_f32_e32 v35, 1.0, v35
	v_add_f32_e32 v36, 1.0, v36
	v_rcp_f32_e32 v35, v35
	v_rcp_f32_e32 v36, v36
	v_mul_f32_e32 v53, v53, v34
	v_add_f32_e32 v34, 1.0, v70
	v_mul_f32_e32 v55, v55, v35
	v_mul_f32_e32 v73, v39, v36
	v_mul_f32_e32 v35, 0xbfb8aa3b, v40
	v_mul_f32_e32 v36, 0xbfb8aa3b, v57
	v_exp_f32_e32 v35, v35
	v_exp_f32_e32 v36, v36
	v_mul_f32_e32 v70, 0xbfb8aa3b, v56
	v_rcp_f32_e32 v34, v34
	v_add_f32_e32 v35, 1.0, v35
	v_add_f32_e32 v36, 1.0, v36
	v_rcp_f32_e32 v35, v35
	v_rcp_f32_e32 v36, v36
	v_exp_f32_e32 v70, v70
	v_mul_f32_e32 v71, v38, v34
	v_mul_f32_e32 v40, v40, v35
	v_mul_f32_e32 v57, v57, v36
	v_mul_f32_e32 v35, 0xbfb8aa3b, v58
	v_mul_f32_e32 v36, 0xbfb8aa3b, v42
	v_exp_f32_e32 v35, v35
	v_exp_f32_e32 v36, v36
	v_add_f32_e32 v34, 1.0, v70
	v_mul_f32_e32 v38, 0xbfb8aa3b, v41
	v_add_f32_e32 v35, 1.0, v35
	v_add_f32_e32 v36, 1.0, v36
	v_rcp_f32_e32 v35, v35
	v_rcp_f32_e32 v36, v36
	v_rcp_f32_e32 v34, v34
	v_exp_f32_e32 v38, v38
	v_mul_f32_e32 v58, v58, v35
	v_mul_f32_e32 v42, v42, v36
	v_mul_f32_e32 v35, 0xbfb8aa3b, v43
	v_mul_f32_e32 v36, 0xbfb8aa3b, v60
	v_exp_f32_e32 v35, v35
	v_exp_f32_e32 v36, v36
	v_mul_f32_e32 v56, v56, v34
	v_add_f32_e32 v34, 1.0, v38
	v_add_f32_e32 v35, 1.0, v35
	v_add_f32_e32 v36, 1.0, v36
	v_rcp_f32_e32 v35, v35
	v_rcp_f32_e32 v36, v36
	v_mul_f32_e32 v38, 0xbfb8aa3b, v59
	v_rcp_f32_e32 v34, v34
	v_mul_f32_e32 v43, v43, v35
	v_mul_f32_e32 v60, v60, v36
	v_mul_f32_e32 v35, 0xbfb8aa3b, v61
	v_mul_f32_e32 v36, 0xbfb8aa3b, v45
	v_exp_f32_e32 v38, v38
	v_exp_f32_e32 v35, v35
	v_exp_f32_e32 v36, v36
	v_mul_f32_e32 v41, v41, v34
	v_add_f32_e32 v34, 1.0, v38
	v_mul_f32_e32 v38, 0xbfb8aa3b, v44
	v_add_f32_e32 v35, 1.0, v35
	v_add_f32_e32 v36, 1.0, v36
	v_rcp_f32_e32 v34, v34
	v_exp_f32_e32 v38, v38
	v_rcp_f32_e32 v35, v35
	v_rcp_f32_e32 v36, v36
	v_mul_f32_e32 v59, v59, v34
	v_add_f32_e32 v34, 1.0, v38
	v_mul_f32_e32 v38, 0xbfb8aa3b, v62
	v_mul_f32_e32 v61, v61, v35
	v_mul_f32_e32 v45, v45, v36
	v_mul_f32_e32 v35, 0xbfb8aa3b, v46
	v_mul_f32_e32 v36, 0xbfb8aa3b, v63
	v_rcp_f32_e32 v34, v34
	v_exp_f32_e32 v38, v38
	v_exp_f32_e32 v35, v35
	v_exp_f32_e32 v36, v36
	v_mul_f32_e32 v44, v44, v34
	v_add_f32_e32 v34, 1.0, v38
	v_add_f32_e32 v35, 1.0, v35
	v_add_f32_e32 v36, 1.0, v36
	v_mul_f32_e32 v38, 0xbfb8aa3b, v47
	v_rcp_f32_e32 v34, v34
	v_rcp_f32_e32 v35, v35
	v_rcp_f32_e32 v36, v36
	v_exp_f32_e32 v38, v38
	v_mul_f32_e32 v62, v62, v34
	v_mul_f32_e32 v46, v46, v35
	v_mul_f32_e32 v63, v63, v36
	v_add_f32_e32 v34, 1.0, v38
	v_mul_f32_e32 v35, 0xbfb8aa3b, v64
	v_mul_f32_e32 v36, 0xbfb8aa3b, v48
	v_rcp_f32_e32 v34, v34
	v_exp_f32_e32 v35, v35
	v_exp_f32_e32 v36, v36
	v_mul_f32_e32 v38, 0xbfb8aa3b, v49
	v_mul_f32_e32 v47, v47, v34
	v_add_f32_e32 v34, 1.0, v35
	v_add_f32_e32 v35, 1.0, v36
	v_mul_f32_e32 v36, 0xbfb8aa3b, v65
	v_exp_f32_e32 v36, v36
	v_exp_f32_e32 v38, v38
	v_rcp_f32_e32 v34, v34
	v_rcp_f32_e32 v35, v35
	v_add_f32_e32 v36, 1.0, v36
	v_add_f32_e32 v38, 1.0, v38
	v_rcp_f32_e32 v36, v36
	v_rcp_f32_e32 v38, v38
	v_mul_f32_e32 v64, v64, v34
	v_mul_f32_e32 v48, v48, v35
	v_permlane32_swap_b32_e32 v50, v68
	v_permlane32_swap_b32_e32 v51, v72
	v_permlane32_swap_b32_e32 v52, v69
	v_permlane32_swap_b32_e32 v53, v37
	v_lshlrev_b32_e32 v34, 1, v100
	v_mov_b32_e32 v35, v99
	v_mul_f32_e32 v65, v65, v36
	v_mul_f32_e32 v49, v49, v38
	v_permlane32_swap_b32_e32 v54, v71
	v_permlane32_swap_b32_e32 v55, v73
	v_permlane32_swap_b32_e32 v56, v40
	v_permlane32_swap_b32_e32 v57, v41
	v_lshl_add_u64 v[38:39], v[66:67], 0, v[34:35]
	v_cvt_pk_bf16_f32 v34, v50, v51
	v_cvt_pk_bf16_f32 v35, v52, v53
	v_cvt_pk_bf16_f32 v36, v68, v72
	v_cvt_pk_bf16_f32 v37, v69, v37
	v_permlane32_swap_b32_e32 v58, v42
	v_permlane32_swap_b32_e32 v59, v43
	v_permlane32_swap_b32_e32 v60, v44
	v_permlane32_swap_b32_e32 v61, v45
	ds_write_b128 v202, v[34:37]
	v_permlane32_swap_b32_e32 v62, v46
	s_nop 0
	v_cvt_pk_bf16_f32 v34, v54, v55
	v_cvt_pk_bf16_f32 v35, v56, v57
	v_cvt_pk_bf16_f32 v36, v71, v73
	v_cvt_pk_bf16_f32 v37, v40, v41
	v_permlane32_swap_b32_e32 v63, v47
	v_permlane32_swap_b32_e32 v64, v48
	v_permlane32_swap_b32_e32 v65, v49
	ds_write_b128 v202, v[34:37] offset:16
	s_nop 1
	v_cvt_pk_bf16_f32 v34, v58, v59
	v_cvt_pk_bf16_f32 v35, v60, v61
	v_cvt_pk_bf16_f32 v36, v42, v43
	v_cvt_pk_bf16_f32 v37, v44, v45
	ds_write_b128 v202, v[34:37] offset:32
	s_nop 1
	v_cvt_pk_bf16_f32 v34, v62, v63
	v_cvt_pk_bf16_f32 v35, v64, v65
	v_cvt_pk_bf16_f32 v36, v46, v47
	v_cvt_pk_bf16_f32 v37, v48, v49
	ds_write_b128 v202, v[34:37] offset:48
	v_lshl_add_u64 v[184:185], v[38:39], 0, v[206:207]
	ds_read_b128 v[176:179], v204
	ds_read_b128 v[180:183], v204 offset:144
	s_waitcnt lgkmcnt(1)
	global_store_dwordx4 v[184:185], v[176:179], off
	ds_read_b128 v[176:179], v204 offset:288
	s_waitcnt lgkmcnt(1)
	global_store_dwordx4 v[184:185], v[180:183], off offset:1024
	ds_read_b128 v[180:183], v204 offset:432
	s_waitcnt lgkmcnt(1)
	global_store_dwordx4 v[184:185], v[176:179], off offset:2048
	s_waitcnt lgkmcnt(0)
	global_store_dwordx4 v[184:185], v[180:183], off offset:3072

.LBB0_324:
	s_andn2_saveexec_b64 s[14:15], s[34:35]
	s_cbranch_execz .LBB0_326
	v_mul_f32_e32 v34, 0xbfb8aa3b, v34
	v_mul_f32_e32 v35, 0xbfb8aa3b, v35
	v_exp_f32_e32 v34, v34
	v_exp_f32_e32 v35, v35
	v_mul_f32_e32 v36, 0xbfb8aa3b, v36
	v_exp_f32_e32 v36, v36
	v_add_f32_e32 v34, 1.0, v34
	v_add_f32_e32 v35, 1.0, v35
	v_rcp_f32_e32 v34, v34
	v_rcp_f32_e32 v35, v35
	v_cmp_gt_i32_e64 s[12:13], s57, v68
	v_mul_f32_e32 v50, v50, v34
	v_mul_f32_e32 v51, v51, v35
	v_add_f32_e32 v34, 1.0, v36
	v_mul_f32_e32 v35, 0xbfb8aa3b, v37
	v_mul_f32_e32 v36, 0xbfb8aa3b, v38
	v_exp_f32_e32 v35, v35
	v_exp_f32_e32 v36, v36
	v_mul_f32_e32 v37, 0xbfb8aa3b, v39
	v_rcp_f32_e32 v34, v34
	v_add_f32_e32 v35, 1.0, v35
	v_add_f32_e32 v36, 1.0, v36
	v_rcp_f32_e32 v35, v35
	v_rcp_f32_e32 v36, v36
	v_exp_f32_e32 v37, v37
	v_mul_f32_e32 v52, v52, v34
	v_mul_f32_e32 v53, v53, v35
	v_mul_f32_e32 v54, v54, v36
	v_mul_f32_e32 v35, 0xbfb8aa3b, v40
	v_mul_f32_e32 v36, 0xbfb8aa3b, v41
	v_exp_f32_e32 v35, v35
	v_exp_f32_e32 v36, v36
	v_add_f32_e32 v34, 1.0, v37
	v_mul_f32_e32 v37, 0xbfb8aa3b, v42
	v_add_f32_e32 v35, 1.0, v35
	v_add_f32_e32 v36, 1.0, v36
	v_rcp_f32_e32 v35, v35
	v_rcp_f32_e32 v36, v36
	v_rcp_f32_e32 v34, v34
	v_exp_f32_e32 v37, v37
	v_mul_f32_e32 v41, v56, v35
	v_mul_f32_e32 v42, v57, v36
	v_mul_f32_e32 v35, 0xbfb8aa3b, v43
	v_mul_f32_e32 v36, 0xbfb8aa3b, v44
	v_exp_f32_e32 v35, v35
	v_exp_f32_e32 v36, v36
	v_mul_f32_e32 v40, v55, v34
	v_add_f32_e32 v34, 1.0, v37
	v_add_f32_e32 v35, 1.0, v35
	v_add_f32_e32 v36, 1.0, v36
	v_mul_f32_e32 v37, 0xbfb8aa3b, v45
	v_rcp_f32_e32 v34, v34
	v_rcp_f32_e32 v35, v35
	v_rcp_f32_e32 v36, v36
	v_exp_f32_e32 v37, v37
	v_mul_f32_e32 v43, v58, v34
	v_mul_f32_e32 v44, v59, v35
	v_mul_f32_e32 v45, v60, v36
	v_add_f32_e32 v34, 1.0, v37
	v_mul_f32_e32 v35, 0xbfb8aa3b, v46
	v_mul_f32_e32 v36, 0xbfb8aa3b, v47
	v_rcp_f32_e32 v34, v34
	v_exp_f32_e32 v35, v35
	v_exp_f32_e32 v36, v36
	v_mul_f32_e32 v38, 0xbfb8aa3b, v49
	v_mul_f32_e32 v37, v61, v34
	v_add_f32_e32 v34, 1.0, v35
	v_add_f32_e32 v35, 1.0, v36
	v_rcp_f32_e32 v35, v35
	v_mul_f32_e32 v36, 0xbfb8aa3b, v48
	v_rcp_f32_e32 v34, v34
	v_exp_f32_e32 v36, v36
	v_exp_f32_e32 v38, v38
	v_mul_f32_e32 v47, v63, v35
	v_add_u32_e32 v35, 0xffffe020, v108
	v_lshrrev_b32_e32 v35, 12, v35
	v_add_f32_e32 v36, 1.0, v36
	v_add_f32_e32 v38, 1.0, v38
	v_mul_f32_e32 v46, v62, v34
	v_ashrrev_i32_e32 v34, 8, v66
	v_add_u32_e32 v35, 32, v35
	v_rcp_f32_e32 v36, v36
	v_rcp_f32_e32 v38, v38
	v_cndmask_b32_e64 v34, v35, v34, s[12:13]
	v_lshlrev_b32_e32 v34, 5, v34
	v_add3_u32 v34, v68, v34, 16
	v_ashrrev_i32_e32 v35, 31, v34
	v_mul_f32_e32 v48, v64, v36
	v_mul_f32_e32 v49, v65, v38
	v_permlane32_swap_b32_e32 v50, v43
	v_permlane32_swap_b32_e32 v51, v44
	v_permlane32_swap_b32_e32 v52, v45
	v_permlane32_swap_b32_e32 v53, v37
	v_lshlrev_b64 v[34:35], 10, v[34:35]
	v_permlane32_swap_b32_e32 v54, v46
	v_permlane32_swap_b32_e32 v40, v47
	v_permlane32_swap_b32_e32 v41, v48
	v_permlane32_swap_b32_e32 v42, v49
	v_lshl_add_u64 v[38:39], v[116:117], 0, v[34:35]
	v_cvt_pk_bf16_f32 v34, v50, v51
	v_cvt_pk_bf16_f32 v35, v52, v53
	v_cvt_pk_bf16_f32 v36, v43, v44
	v_cvt_pk_bf16_f32 v37, v45, v37
	ds_write_b128 v203, v[34:37]
	s_nop 1
	v_cvt_pk_bf16_f32 v34, v54, v40
	v_cvt_pk_bf16_f32 v35, v41, v42
	v_cvt_pk_bf16_f32 v36, v46, v47
	v_cvt_pk_bf16_f32 v37, v48, v49
	ds_write_b128 v203, v[34:37] offset:16
	v_lshl_add_u64 v[184:185], v[38:39], 0, v[210:211]
	ds_read_b128 v[176:179], v205
	ds_read_b128 v[180:183], v205 offset:144
	s_waitcnt lgkmcnt(1)
	global_store_dwordx4 v[184:185], v[176:179], off
	s_waitcnt lgkmcnt(0)
	global_store_dwordx4 v[184:185], v[180:183], off offset:1024

.LBB0_361:
	s_or_b64 exec, exec, s[6:7]
	v_pk_mul_f32 v[6:7], v[104:105], v[6:7]
	v_pk_mul_f32 v[8:9], v[104:105], v[8:9]
	v_pk_mul_f32 v[2:3], v[104:105], v[2:3]
	v_cvt_pk_bf16_f32 v6, v6, v7
	v_cvt_pk_bf16_f32 v7, v8, v9
	v_cvt_pk_bf16_f32 v8, v2, v3
	v_pk_mul_f32 v[2:3], v[104:105], v[4:5]
	s_and_b64 s[4:5], s[4:5], s[8:9]
	v_cvt_pk_bf16_f32 v9, v2, v3
	ds_write_b128 v202, v[6:9] offset:48
	ds_read_b128 v[176:179], v204
	ds_read_b128 v[180:183], v204 offset:144
	s_cmp_lg_u64 s[98:99], 0
	s_cbranch_scc0 .Lg1co_k6
	v_lshl_add_u64 v[184:185], v[40:41], 0, v[206:207]
	s_waitcnt lgkmcnt(1)
	global_store_dwordx4 v[184:185], v[176:179], off
	ds_read_b128 v[176:179], v204 offset:288
	s_waitcnt lgkmcnt(1)
	global_store_dwordx4 v[184:185], v[180:183], off offset:1024
	ds_read_b128 v[180:183], v204 offset:432
	s_waitcnt lgkmcnt(1)
	global_store_dwordx4 v[184:185], v[176:179], off offset:2048
	s_waitcnt lgkmcnt(0)
	global_store_dwordx4 v[184:185], v[180:183], off offset:3072
	s_branch .Lg1co_e6
.Lg1co_k6:
	v_lshl_add_u64 v[184:185], v[40:41], 0, v[208:209]
	s_waitcnt lgkmcnt(1)
	global_store_dwordx4 v[184:185], v[176:179], off
	ds_read_b128 v[176:179], v204 offset:288
	s_waitcnt lgkmcnt(1)
	global_store_dwordx4 v[184:185], v[180:183], off offset:128
	ds_read_b128 v[180:183], v204 offset:432
	s_waitcnt lgkmcnt(1)
	global_store_dwordx4 v[184:185], v[176:179], off offset:256
	s_waitcnt lgkmcnt(0)
	global_store_dwordx4 v[184:185], v[180:183], off offset:384

.LBB0_380:
	s_andn2_saveexec_b64 s[4:5], s[14:15]
	s_cbranch_execz .LBB0_382
	v_ashrrev_i32_e32 v37, 31, v36
	v_lshlrev_b64 v[34:35], 10, v[36:37]
	v_mul_f32_e32 v37, 0xbfb8aa3b, v18
	v_mul_f32_e32 v38, 0xbfb8aa3b, v3
	v_exp_f32_e32 v37, v37
	v_exp_f32_e32 v38, v38
	v_mul_f32_e32 v36, 0xbfb8aa3b, v2
	v_exp_f32_e32 v36, v36
	v_add_f32_e32 v37, 1.0, v37
	v_add_f32_e32 v38, 1.0, v38
	v_rcp_f32_e32 v37, v37
	v_rcp_f32_e32 v38, v38
	v_add_f32_e32 v36, 1.0, v36
	v_mul_f32_e32 v39, 0xbfb8aa3b, v19
	v_mul_f32_e32 v18, v18, v37
	v_mul_f32_e32 v3, v3, v38
	v_mul_f32_e32 v37, 0xbfb8aa3b, v4
	v_mul_f32_e32 v38, 0xbfb8aa3b, v20
	v_exp_f32_e32 v37, v37
	v_exp_f32_e32 v38, v38
	v_rcp_f32_e32 v36, v36
	v_exp_f32_e32 v39, v39
	v_add_f32_e32 v37, 1.0, v37
	v_add_f32_e32 v38, 1.0, v38
	v_rcp_f32_e32 v37, v37
	v_rcp_f32_e32 v38, v38
	v_mul_f32_e32 v2, v2, v36
	v_add_f32_e32 v36, 1.0, v39
	v_mul_f32_e32 v39, 0xbfb8aa3b, v5
	v_mul_f32_e32 v4, v4, v37
	v_mul_f32_e32 v20, v20, v38
	v_mul_f32_e32 v37, 0xbfb8aa3b, v21
	v_mul_f32_e32 v38, 0xbfb8aa3b, v6
	v_rcp_f32_e32 v36, v36
	v_exp_f32_e32 v39, v39
	v_exp_f32_e32 v37, v37
	v_exp_f32_e32 v38, v38
	v_mul_f32_e32 v19, v19, v36
	v_add_f32_e32 v36, 1.0, v39
	v_add_f32_e32 v37, 1.0, v37
	v_add_f32_e32 v38, 1.0, v38
	v_rcp_f32_e32 v36, v36
	v_rcp_f32_e32 v37, v37
	v_rcp_f32_e32 v38, v38
	v_mul_f32_e32 v39, 0xbfb8aa3b, v22
	v_mul_f32_e32 v5, v5, v36
	v_mul_f32_e32 v21, v21, v37
	v_mul_f32_e32 v36, v6, v38
	v_mul_f32_e32 v37, 0xbfb8aa3b, v7
	v_mul_f32_e32 v38, 0xbfb8aa3b, v23
	v_exp_f32_e32 v37, v37
	v_exp_f32_e32 v38, v38
	v_exp_f32_e32 v39, v39
	v_lshl_add_u64 v[34:35], v[114:115], 0, v[34:35]
	v_add_f32_e32 v37, 1.0, v37
	v_add_f32_e32 v38, 1.0, v38
	v_rcp_f32_e32 v37, v37
	v_rcp_f32_e32 v38, v38
	v_add_f32_e32 v6, 1.0, v39
	v_mul_f32_e32 v39, 0xbfb8aa3b, v8
	v_mul_f32_e32 v37, v7, v37
	v_mul_f32_e32 v23, v23, v38
	v_mul_f32_e32 v7, 0xbfb8aa3b, v24
	v_mul_f32_e32 v38, 0xbfb8aa3b, v9
	v_exp_f32_e32 v7, v7
	v_exp_f32_e32 v38, v38
	v_rcp_f32_e32 v6, v6
	v_exp_f32_e32 v39, v39
	v_add_f32_e32 v7, 1.0, v7
	v_add_f32_e32 v38, 1.0, v38
	v_rcp_f32_e32 v7, v7
	v_rcp_f32_e32 v38, v38
	v_mul_f32_e32 v22, v22, v6
	v_add_f32_e32 v6, 1.0, v39
	v_mul_f32_e32 v24, v24, v7
	v_mul_f32_e32 v9, v9, v38
	v_mul_f32_e32 v7, 0xbfb8aa3b, v10
	v_mul_f32_e32 v38, 0xbfb8aa3b, v26
	v_exp_f32_e32 v7, v7
	v_exp_f32_e32 v38, v38
	v_mul_f32_e32 v39, 0xbfb8aa3b, v25
	v_rcp_f32_e32 v6, v6
	v_add_f32_e32 v7, 1.0, v7
	v_add_f32_e32 v38, 1.0, v38
	v_rcp_f32_e32 v7, v7
	v_rcp_f32_e32 v38, v38
	v_exp_f32_e32 v39, v39
	v_mul_f32_e32 v8, v8, v6
	v_mul_f32_e32 v10, v10, v7
	v_mul_f32_e32 v26, v26, v38
	v_mul_f32_e32 v7, 0xbfb8aa3b, v27
	v_mul_f32_e32 v38, 0xbfb8aa3b, v12
	v_exp_f32_e32 v7, v7
	v_exp_f32_e32 v38, v38
	v_add_f32_e32 v6, 1.0, v39
	v_mul_f32_e32 v39, 0xbfb8aa3b, v11
	v_add_f32_e32 v7, 1.0, v7
	v_add_f32_e32 v38, 1.0, v38
	v_rcp_f32_e32 v7, v7
	v_rcp_f32_e32 v38, v38
	v_rcp_f32_e32 v6, v6
	v_exp_f32_e32 v39, v39
	v_mul_f32_e32 v27, v27, v7
	v_mul_f32_e32 v12, v12, v38
	v_mul_f32_e32 v7, 0xbfb8aa3b, v13
	v_mul_f32_e32 v38, 0xbfb8aa3b, v29
	v_exp_f32_e32 v7, v7
	v_exp_f32_e32 v38, v38
	v_mul_f32_e32 v25, v25, v6
	v_add_f32_e32 v6, 1.0, v39
	v_mul_f32_e32 v39, 0xbfb8aa3b, v28
	v_add_f32_e32 v7, 1.0, v7
	v_add_f32_e32 v38, 1.0, v38
	v_rcp_f32_e32 v6, v6
	v_exp_f32_e32 v39, v39
	v_rcp_f32_e32 v7, v7
	v_rcp_f32_e32 v38, v38
	v_mul_f32_e32 v11, v11, v6
	v_add_f32_e32 v6, 1.0, v39
	v_mul_f32_e32 v39, 0xbfb8aa3b, v14
	v_mul_f32_e32 v13, v13, v7
	v_mul_f32_e32 v29, v29, v38
	v_mul_f32_e32 v7, 0xbfb8aa3b, v30
	v_mul_f32_e32 v38, 0xbfb8aa3b, v15
	v_rcp_f32_e32 v6, v6
	v_exp_f32_e32 v39, v39
	v_exp_f32_e32 v7, v7
	v_exp_f32_e32 v38, v38
	v_mul_f32_e32 v28, v28, v6
	v_add_f32_e32 v6, 1.0, v39
	v_add_f32_e32 v7, 1.0, v7
	v_add_f32_e32 v38, 1.0, v38
	v_mul_f32_e32 v39, 0xbfb8aa3b, v31
	v_rcp_f32_e32 v6, v6
	v_rcp_f32_e32 v7, v7
	v_rcp_f32_e32 v38, v38
	v_exp_f32_e32 v39, v39
	v_mul_f32_e32 v14, v14, v6
	v_mul_f32_e32 v30, v30, v7
	v_mul_f32_e32 v15, v15, v38
	v_add_f32_e32 v6, 1.0, v39
	v_mul_f32_e32 v7, 0xbfb8aa3b, v16
	v_mul_f32_e32 v38, 0xbfb8aa3b, v32
	v_rcp_f32_e32 v6, v6
	v_exp_f32_e32 v7, v7
	v_exp_f32_e32 v38, v38
	v_mul_f32_e32 v39, 0xbfb8aa3b, v33
	v_mul_f32_e32 v31, v31, v6
	v_add_f32_e32 v6, 1.0, v7
	v_add_f32_e32 v7, 1.0, v38
	v_mul_f32_e32 v38, 0xbfb8aa3b, v17
	v_exp_f32_e32 v38, v38
	v_exp_f32_e32 v39, v39
	v_rcp_f32_e32 v6, v6
	v_rcp_f32_e32 v7, v7
	v_add_f32_e32 v38, 1.0, v38
	v_add_f32_e32 v39, 1.0, v39
	v_rcp_f32_e32 v38, v38
	v_rcp_f32_e32 v39, v39
	v_cndmask_b32_e32 v98, v133, v134, vcc
	v_lshl_add_u64 v[34:35], v[34:35], 0, v[98:99]
	v_permlane32_swap_b32_e32 v2, v18
	v_permlane32_swap_b32_e32 v3, v19
	v_permlane32_swap_b32_e32 v4, v20
	v_permlane32_swap_b32_e32 v5, v21
	v_lshlrev_b32_e32 v98, 1, v100
	v_mul_f32_e32 v16, v16, v6
	v_mul_f32_e32 v32, v32, v7
	v_permlane32_swap_b32_e32 v36, v22
	v_permlane32_swap_b32_e32 v37, v23
	v_permlane32_swap_b32_e32 v8, v24
	v_permlane32_swap_b32_e32 v9, v25
	v_lshl_add_u64 v[6:7], v[34:35], 0, v[98:99]
	v_cvt_pk_bf16_f32 v2, v2, v3
	v_cvt_pk_bf16_f32 v3, v4, v5
	v_cvt_pk_bf16_f32 v4, v18, v19
	v_cvt_pk_bf16_f32 v5, v20, v21
	v_mul_f32_e32 v17, v17, v38
	v_mul_f32_e32 v33, v33, v39
	v_permlane32_swap_b32_e32 v10, v26
	v_permlane32_swap_b32_e32 v11, v27
	v_permlane32_swap_b32_e32 v12, v28
	v_permlane32_swap_b32_e32 v13, v29
	ds_write_b128 v202, v[2:5]
	v_permlane32_swap_b32_e32 v14, v30
	s_nop 0
	v_cvt_pk_bf16_f32 v2, v36, v37
	v_cvt_pk_bf16_f32 v3, v8, v9
	v_cvt_pk_bf16_f32 v4, v22, v23
	v_cvt_pk_bf16_f32 v5, v24, v25
	v_permlane32_swap_b32_e32 v15, v31
	v_permlane32_swap_b32_e32 v16, v32
	v_permlane32_swap_b32_e32 v17, v33
	ds_write_b128 v202, v[2:5] offset:16
	s_nop 1
	v_cvt_pk_bf16_f32 v2, v10, v11
	v_cvt_pk_bf16_f32 v3, v12, v13
	v_cvt_pk_bf16_f32 v4, v26, v27
	v_cvt_pk_bf16_f32 v5, v28, v29
	ds_write_b128 v202, v[2:5] offset:32
	s_nop 1
	v_cvt_pk_bf16_f32 v2, v14, v15
	v_cvt_pk_bf16_f32 v3, v16, v17
	v_cvt_pk_bf16_f32 v4, v30, v31
	v_cvt_pk_bf16_f32 v5, v32, v33
	ds_write_b128 v202, v[2:5] offset:48
	v_lshl_add_u64 v[184:185], v[6:7], 0, v[206:207]
	ds_read_b128 v[176:179], v204
	ds_read_b128 v[180:183], v204 offset:144
	s_waitcnt lgkmcnt(1)
	global_store_dwordx4 v[184:185], v[176:179], off
	ds_read_b128 v[176:179], v204 offset:288
	s_waitcnt lgkmcnt(1)
	global_store_dwordx4 v[184:185], v[180:183], off offset:1024
	ds_read_b128 v[180:183], v204 offset:432
	s_waitcnt lgkmcnt(1)
	global_store_dwordx4 v[184:185], v[176:179], off offset:2048
	s_waitcnt lgkmcnt(0)
	global_store_dwordx4 v[184:185], v[180:183], off offset:3072

.LBB0_383:
	v_mul_f32_e32 v18, 0xbfb8aa3b, v18
	v_mul_f32_e32 v19, 0xbfb8aa3b, v19
	v_exp_f32_e32 v18, v18
	v_exp_f32_e32 v19, v19
	v_mul_f32_e32 v20, 0xbfb8aa3b, v20
	v_exp_f32_e32 v20, v20
	v_add_f32_e32 v18, 1.0, v18
	v_add_f32_e32 v19, 1.0, v19
	v_rcp_f32_e32 v18, v18
	v_rcp_f32_e32 v19, v19
	v_cmp_gt_i32_e32 vcc, s57, v36
	v_mul_f32_e32 v18, v2, v18
	v_mul_f32_e32 v19, v3, v19
	v_add_f32_e32 v2, 1.0, v20
	v_mul_f32_e32 v3, 0xbfb8aa3b, v21
	v_mul_f32_e32 v20, 0xbfb8aa3b, v22
	v_exp_f32_e32 v3, v3
	v_exp_f32_e32 v20, v20
	v_mul_f32_e32 v21, 0xbfb8aa3b, v23
	v_rcp_f32_e32 v2, v2
	v_add_f32_e32 v3, 1.0, v3
	v_add_f32_e32 v20, 1.0, v20
	v_rcp_f32_e32 v3, v3
	v_rcp_f32_e32 v20, v20
	v_exp_f32_e32 v21, v21
	v_mul_f32_e32 v4, v4, v2
	v_mul_f32_e32 v5, v5, v3
	v_mul_f32_e32 v20, v6, v20
	v_mul_f32_e32 v3, 0xbfb8aa3b, v24
	v_mul_f32_e32 v6, 0xbfb8aa3b, v25
	v_exp_f32_e32 v3, v3
	v_exp_f32_e32 v6, v6
	v_add_f32_e32 v2, 1.0, v21
	v_mul_f32_e32 v21, 0xbfb8aa3b, v26
	v_add_f32_e32 v3, 1.0, v3
	v_add_f32_e32 v6, 1.0, v6
	v_rcp_f32_e32 v3, v3
	v_rcp_f32_e32 v6, v6
	v_rcp_f32_e32 v2, v2
	v_exp_f32_e32 v21, v21
	v_mul_f32_e32 v8, v8, v3
	v_mul_f32_e32 v9, v9, v6
	v_mul_f32_e32 v3, 0xbfb8aa3b, v27
	v_mul_f32_e32 v6, 0xbfb8aa3b, v28
	v_exp_f32_e32 v3, v3
	v_exp_f32_e32 v6, v6
	v_mul_f32_e32 v22, v7, v2
	v_add_f32_e32 v2, 1.0, v21
	v_add_f32_e32 v3, 1.0, v3
	v_add_f32_e32 v6, 1.0, v6
	v_mul_f32_e32 v7, 0xbfb8aa3b, v29
	v_rcp_f32_e32 v2, v2
	v_rcp_f32_e32 v3, v3
	v_rcp_f32_e32 v6, v6
	v_exp_f32_e32 v7, v7
	v_mul_f32_e32 v10, v10, v2
	v_mul_f32_e32 v11, v11, v3
	v_mul_f32_e32 v12, v12, v6
	v_add_f32_e32 v2, 1.0, v7
	v_mul_f32_e32 v3, 0xbfb8aa3b, v30
	v_mul_f32_e32 v6, 0xbfb8aa3b, v31
	v_rcp_f32_e32 v2, v2
	v_exp_f32_e32 v3, v3
	v_exp_f32_e32 v6, v6
	v_mul_f32_e32 v7, 0xbfb8aa3b, v33
	v_mul_f32_e32 v13, v13, v2
	v_add_f32_e32 v2, 1.0, v3
	v_add_f32_e32 v3, 1.0, v6
	v_rcp_f32_e32 v3, v3
	v_mul_f32_e32 v6, 0xbfb8aa3b, v32
	v_rcp_f32_e32 v2, v2
	v_exp_f32_e32 v6, v6
	v_exp_f32_e32 v7, v7
	v_mul_f32_e32 v15, v15, v3
	v_add_u32_e32 v3, 0xffffe040, v108
	v_lshrrev_b32_e32 v3, 12, v3
	v_add_f32_e32 v6, 1.0, v6
	v_add_f32_e32 v7, 1.0, v7
	v_mul_f32_e32 v14, v14, v2
	v_ashrrev_i32_e32 v2, 8, v34
	v_add_u32_e32 v3, 32, v3
	v_rcp_f32_e32 v6, v6
	v_rcp_f32_e32 v7, v7
	v_cndmask_b32_e32 v2, v3, v2, vcc
	v_lshlrev_b32_e32 v2, 5, v2
	v_add3_u32 v2, v36, v2, 16
	v_ashrrev_i32_e32 v3, 31, v2
	v_mul_f32_e32 v16, v16, v6
	v_mul_f32_e32 v17, v17, v7
	v_permlane32_swap_b32_e32 v18, v10
	v_permlane32_swap_b32_e32 v19, v11
	v_permlane32_swap_b32_e32 v4, v12
	v_permlane32_swap_b32_e32 v5, v13
	v_lshlrev_b64 v[2:3], 10, v[2:3]
	v_permlane32_swap_b32_e32 v20, v14
	v_permlane32_swap_b32_e32 v22, v15
	v_permlane32_swap_b32_e32 v8, v16
	v_permlane32_swap_b32_e32 v9, v17
	v_lshl_add_u64 v[6:7], v[116:117], 0, v[2:3]
	v_cvt_pk_bf16_f32 v2, v18, v19
	v_cvt_pk_bf16_f32 v3, v4, v5
	v_cvt_pk_bf16_f32 v4, v10, v11
	v_cvt_pk_bf16_f32 v5, v12, v13
	ds_write_b128 v203, v[2:5]
	s_nop 1
	v_cvt_pk_bf16_f32 v2, v20, v22
	v_cvt_pk_bf16_f32 v3, v8, v9
	v_cvt_pk_bf16_f32 v4, v14, v15
	v_cvt_pk_bf16_f32 v5, v16, v17
	ds_write_b128 v203, v[2:5] offset:16
	v_lshl_add_u64 v[184:185], v[6:7], 0, v[210:211]
	ds_read_b128 v[176:179], v205
	ds_read_b128 v[180:183], v205 offset:144
	s_waitcnt lgkmcnt(1)
	global_store_dwordx4 v[184:185], v[176:179], off
	s_waitcnt lgkmcnt(0)
	global_store_dwordx4 v[184:185], v[180:183], off offset:1024
	s_branch .LBB0_204
